# B-pair traversal direction alternates between consecutive MFMA segments (P1 0..3, P2 3..0), otherwise as boustrophedon version
# baseline (speedup 1.0000x reference)
.LBB0_411:
	s_add_u32 s16, s14, 0xfffc0080
	s_addc_u32 s17, s15, -1
	s_add_i32 s51, 0, 0x10000
	s_cmp_eq_u32 s50, 12
	s_cselect_b32 s21, s9, s17
	s_cselect_b32 s20, s46, s16
	s_cselect_b32 s17, s5, s49
	s_cselect_b32 s16, s47, s48
	s_add_i32 s54, 0, 0x14000
	v_add_u32_e32 v154, s51, v181
	v_add_u32_e32 v162, s54, v181
	ds_read_b128 v[130:133], v154
	ds_read_b128 v[134:137], v154 offset:1024
	ds_read_b128 v[150:153], v154 offset:2048
	ds_read_b128 v[154:157], v154 offset:3072
	ds_read_b128 v[158:161], v162
	ds_read_b128 v[174:177], v162 offset:1024
	ds_read_b128 v[186:189], v162 offset:2048
	ds_read_b128 v[190:193], v162 offset:3072
	s_add_i32 m0, s26, 0xc000
	ds_read_b128 v[194:197], v184
	ds_read_b128 v[198:201], v184 offset:1024
	ds_read_b128 v[202:205], v184 offset:2048
	ds_read_b128 v[206:209], v184 offset:3072
	ds_read_b128 v[224:227], v184 offset:4096
	ds_read_b128 v[228:231], v184 offset:5120
	ds_read_b128 v[232:235], v184 offset:6144
	ds_read_b128 v[236:239], v184 offset:7168
	global_load_lds_dwordx4 v146, s[14:15]
	s_add_i32 m0, s26, 0xe000
	s_nop 0
	global_load_lds_dwordx4 v148, s[14:15]
	s_waitcnt vmcnt(8)
	s_waitcnt lgkmcnt(0)
	s_barrier
	s_setprio 1
	s_waitcnt lgkmcnt(0)
	v_mfma_i32_16x16x64_i8 v[126:129], v[130:133], v[194:197], v[126:129]
	v_mfma_i32_16x16x64_i8 v[126:129], v[134:137], v[198:201], v[126:129]
	v_mfma_i32_16x16x64_i8 v[110:113], v[130:133], v[202:205], v[110:113]
	v_mfma_i32_16x16x64_i8 v[110:113], v[134:137], v[206:209], v[110:113]
	v_mfma_i32_16x16x64_i8 v[94:97], v[130:133], v[224:227], v[94:97]
	v_mfma_i32_16x16x64_i8 v[94:97], v[134:137], v[228:231], v[94:97]
	v_mfma_i32_16x16x64_i8 v[78:81], v[130:133], v[232:235], v[78:81]
	v_mfma_i32_16x16x64_i8 v[78:81], v[134:137], v[236:239], v[78:81]
	v_mfma_i32_16x16x64_i8 v[70:73], v[150:153], v[232:235], v[70:73]
	v_mfma_i32_16x16x64_i8 v[70:73], v[154:157], v[236:239], v[70:73]
	v_mfma_i32_16x16x64_i8 v[86:89], v[150:153], v[224:227], v[86:89]
	v_mfma_i32_16x16x64_i8 v[86:89], v[154:157], v[228:231], v[86:89]
	v_mfma_i32_16x16x64_i8 v[102:105], v[150:153], v[202:205], v[102:105]
	v_mfma_i32_16x16x64_i8 v[102:105], v[154:157], v[206:209], v[102:105]
	v_mfma_i32_16x16x64_i8 v[122:125], v[150:153], v[194:197], v[122:125]
	v_mfma_i32_16x16x64_i8 v[122:125], v[154:157], v[198:201], v[122:125]
	v_mfma_i32_16x16x64_i8 v[118:121], v[158:161], v[194:197], v[118:121]
	v_mfma_i32_16x16x64_i8 v[118:121], v[174:177], v[198:201], v[118:121]
	v_mfma_i32_16x16x64_i8 v[106:109], v[158:161], v[202:205], v[106:109]
	v_mfma_i32_16x16x64_i8 v[106:109], v[174:177], v[206:209], v[106:109]
	v_mfma_i32_16x16x64_i8 v[90:93], v[158:161], v[224:227], v[90:93]
	v_mfma_i32_16x16x64_i8 v[90:93], v[174:177], v[228:231], v[90:93]
	v_mfma_i32_16x16x64_i8 v[74:77], v[158:161], v[232:235], v[74:77]
	v_mfma_i32_16x16x64_i8 v[74:77], v[174:177], v[236:239], v[74:77]
	v_mfma_i32_16x16x64_i8 v[66:69], v[186:189], v[232:235], v[66:69]
	v_mfma_i32_16x16x64_i8 v[66:69], v[190:193], v[236:239], v[66:69]
	v_mfma_i32_16x16x64_i8 v[82:85], v[186:189], v[224:227], v[82:85]
	v_mfma_i32_16x16x64_i8 v[82:85], v[190:193], v[228:231], v[82:85]
	v_mfma_i32_16x16x64_i8 v[98:101], v[186:189], v[202:205], v[98:101]
	v_mfma_i32_16x16x64_i8 v[98:101], v[190:193], v[206:209], v[98:101]
	v_mfma_i32_16x16x64_i8 v[114:117], v[186:189], v[194:197], v[114:117]
	v_mfma_i32_16x16x64_i8 v[114:117], v[190:193], v[198:201], v[114:117]
	s_setprio 0
	s_barrier
	s_add_i32 s51, s51, s33
	v_lshl_add_u64 v[162:163], s[16:17], 0, v[0:1]
	s_mov_b32 m0, s51
	ds_read_b128 v[194:197], v184 offset:16384
	ds_read_b128 v[198:201], v184 offset:17408
	ds_read_b128 v[202:205], v184 offset:18432
	ds_read_b128 v[206:209], v184 offset:19456
	ds_read_b128 v[224:227], v184 offset:20480
	ds_read_b128 v[228:231], v184 offset:21504
	ds_read_b128 v[232:235], v184 offset:22528
	ds_read_b128 v[236:239], v184 offset:23552
	global_load_lds_dwordx4 v[162:163], off
	s_add_i32 m0, s51, 0x2000
	s_add_u32 s52, s16, 0x40000
	v_lshl_add_u64 v[164:165], s[16:17], 0, v[138:139]
	s_addc_u32 s53, s17, 0
	s_add_i32 s51, s54, s33
	global_load_lds_dwordx4 v[164:165], off
	s_mov_b32 m0, s51
	v_lshl_add_u64 v[168:169], s[20:21], 0, v[140:141]
	global_load_lds_dwordx4 v0, s[52:53]
	s_add_i32 m0, s51, 0x2000
	s_nop 0
	global_load_lds_dwordx4 v138, s[52:53]
	v_lshl_add_u64 v[166:167], s[20:21], 0, v[142:143]
	s_mov_b32 m0, s26
	s_nop 0
	global_load_lds_dwordx4 v[166:167], off
	s_mov_b32 m0, s27
	s_nop 0
	global_load_lds_dwordx4 v[168:169], off
	s_waitcnt vmcnt(8)
	s_waitcnt lgkmcnt(0)
	s_barrier
	s_setprio 1
	s_waitcnt lgkmcnt(0)
	v_mfma_i32_16x16x64_i8 v[50:53], v[186:189], v[194:197], v[50:53]
	v_mfma_i32_16x16x64_i8 v[50:53], v[190:193], v[198:201], v[50:53]
	v_mfma_i32_16x16x64_i8 v[34:37], v[186:189], v[202:205], v[34:37]
	v_mfma_i32_16x16x64_i8 v[34:37], v[190:193], v[206:209], v[34:37]
	v_mfma_i32_16x16x64_i8 v[18:21], v[186:189], v[224:227], v[18:21]
	v_mfma_i32_16x16x64_i8 v[18:21], v[190:193], v[228:231], v[18:21]
	v_mfma_i32_16x16x64_i8 v[2:5], v[186:189], v[232:235], v[2:5]
	v_mfma_i32_16x16x64_i8 v[2:5], v[190:193], v[236:239], v[2:5]
	v_mfma_i32_16x16x64_i8 v[10:13], v[158:161], v[232:235], v[10:13]
	v_mfma_i32_16x16x64_i8 v[10:13], v[174:177], v[236:239], v[10:13]
	v_mfma_i32_16x16x64_i8 v[26:29], v[158:161], v[224:227], v[26:29]
	v_mfma_i32_16x16x64_i8 v[26:29], v[174:177], v[228:231], v[26:29]
	v_mfma_i32_16x16x64_i8 v[42:45], v[158:161], v[202:205], v[42:45]
	v_mfma_i32_16x16x64_i8 v[42:45], v[174:177], v[206:209], v[42:45]
	v_mfma_i32_16x16x64_i8 v[58:61], v[158:161], v[194:197], v[58:61]
	v_mfma_i32_16x16x64_i8 v[58:61], v[174:177], v[198:201], v[58:61]
	v_mfma_i32_16x16x64_i8 v[54:57], v[150:153], v[194:197], v[54:57]
	v_mfma_i32_16x16x64_i8 v[54:57], v[154:157], v[198:201], v[54:57]
	v_mfma_i32_16x16x64_i8 v[38:41], v[150:153], v[202:205], v[38:41]
	v_mfma_i32_16x16x64_i8 v[38:41], v[154:157], v[206:209], v[38:41]
	v_mfma_i32_16x16x64_i8 v[22:25], v[150:153], v[224:227], v[22:25]
	v_mfma_i32_16x16x64_i8 v[22:25], v[154:157], v[228:231], v[22:25]
	v_mfma_i32_16x16x64_i8 v[6:9], v[150:153], v[232:235], v[6:9]
	v_mfma_i32_16x16x64_i8 v[6:9], v[154:157], v[236:239], v[6:9]
	v_mfma_i32_16x16x64_i8 v[14:17], v[130:133], v[232:235], v[14:17]
	v_mfma_i32_16x16x64_i8 v[14:17], v[134:137], v[236:239], v[14:17]
	v_mfma_i32_16x16x64_i8 v[30:33], v[130:133], v[224:227], v[30:33]
	v_mfma_i32_16x16x64_i8 v[30:33], v[134:137], v[228:231], v[30:33]
	v_mfma_i32_16x16x64_i8 v[46:49], v[130:133], v[202:205], v[46:49]
	v_mfma_i32_16x16x64_i8 v[46:49], v[134:137], v[206:209], v[46:49]
	v_mfma_i32_16x16x64_i8 v[62:65], v[130:133], v[194:197], v[62:65]
	v_mfma_i32_16x16x64_i8 v[62:65], v[134:137], v[198:201], v[62:65]
	s_setprio 0
	s_barrier
	s_add_i32 s51, 0, 0x18000
	s_add_i32 s52, 0, 0x1c000
	v_add_u32_e32 v154, s51, v181
	v_add_u32_e32 v170, s52, v181
	ds_read_b128 v[130:133], v154
	ds_read_b128 v[134:137], v154 offset:1024
	ds_read_b128 v[150:153], v154 offset:2048
	ds_read_b128 v[154:157], v154 offset:3072
	ds_read_b128 v[158:161], v170
	ds_read_b128 v[174:177], v170 offset:1024
	ds_read_b128 v[186:189], v170 offset:2048
	ds_read_b128 v[190:193], v170 offset:3072
	s_add_u32 s20, s20, 0x40000
	s_addc_u32 s21, s21, 0
	s_mov_b32 m0, s28
	ds_read_b128 v[194:197], v184 offset:32768
	ds_read_b128 v[198:201], v184 offset:33792
	ds_read_b128 v[202:205], v184 offset:34816
	ds_read_b128 v[206:209], v184 offset:35840
	ds_read_b128 v[224:227], v184 offset:36864
	ds_read_b128 v[228:231], v184 offset:37888
	ds_read_b128 v[232:235], v184 offset:38912
	ds_read_b128 v[236:239], v184 offset:39936
	global_load_lds_dwordx4 v142, s[20:21]
	s_mov_b32 m0, s29
	s_nop 0
	global_load_lds_dwordx4 v140, s[20:21]
	s_waitcnt vmcnt(8)
	s_waitcnt lgkmcnt(0)
	s_barrier
	s_setprio 1
	s_waitcnt lgkmcnt(0)
	v_mfma_i32_16x16x64_i8 v[126:129], v[130:133], v[194:197], v[126:129]
	v_mfma_i32_16x16x64_i8 v[126:129], v[134:137], v[198:201], v[126:129]
	v_mfma_i32_16x16x64_i8 v[110:113], v[130:133], v[202:205], v[110:113]
	v_mfma_i32_16x16x64_i8 v[110:113], v[134:137], v[206:209], v[110:113]
	v_mfma_i32_16x16x64_i8 v[94:97], v[130:133], v[224:227], v[94:97]
	v_mfma_i32_16x16x64_i8 v[94:97], v[134:137], v[228:231], v[94:97]
	v_mfma_i32_16x16x64_i8 v[78:81], v[130:133], v[232:235], v[78:81]
	v_mfma_i32_16x16x64_i8 v[78:81], v[134:137], v[236:239], v[78:81]
	v_mfma_i32_16x16x64_i8 v[70:73], v[150:153], v[232:235], v[70:73]
	v_mfma_i32_16x16x64_i8 v[70:73], v[154:157], v[236:239], v[70:73]
	v_mfma_i32_16x16x64_i8 v[86:89], v[150:153], v[224:227], v[86:89]
	v_mfma_i32_16x16x64_i8 v[86:89], v[154:157], v[228:231], v[86:89]
	v_mfma_i32_16x16x64_i8 v[102:105], v[150:153], v[202:205], v[102:105]
	v_mfma_i32_16x16x64_i8 v[102:105], v[154:157], v[206:209], v[102:105]
	v_mfma_i32_16x16x64_i8 v[122:125], v[150:153], v[194:197], v[122:125]
	v_mfma_i32_16x16x64_i8 v[122:125], v[154:157], v[198:201], v[122:125]
	v_mfma_i32_16x16x64_i8 v[118:121], v[158:161], v[194:197], v[118:121]
	v_mfma_i32_16x16x64_i8 v[118:121], v[174:177], v[198:201], v[118:121]
	v_mfma_i32_16x16x64_i8 v[106:109], v[158:161], v[202:205], v[106:109]
	v_mfma_i32_16x16x64_i8 v[106:109], v[174:177], v[206:209], v[106:109]
	v_mfma_i32_16x16x64_i8 v[90:93], v[158:161], v[224:227], v[90:93]
	v_mfma_i32_16x16x64_i8 v[90:93], v[174:177], v[228:231], v[90:93]
	v_mfma_i32_16x16x64_i8 v[74:77], v[158:161], v[232:235], v[74:77]
	v_mfma_i32_16x16x64_i8 v[74:77], v[174:177], v[236:239], v[74:77]
	v_mfma_i32_16x16x64_i8 v[66:69], v[186:189], v[232:235], v[66:69]
	v_mfma_i32_16x16x64_i8 v[66:69], v[190:193], v[236:239], v[66:69]
	v_mfma_i32_16x16x64_i8 v[82:85], v[186:189], v[224:227], v[82:85]
	v_mfma_i32_16x16x64_i8 v[82:85], v[190:193], v[228:231], v[82:85]
	v_mfma_i32_16x16x64_i8 v[98:101], v[186:189], v[202:205], v[98:101]
	v_mfma_i32_16x16x64_i8 v[98:101], v[190:193], v[206:209], v[98:101]
	v_mfma_i32_16x16x64_i8 v[114:117], v[186:189], v[194:197], v[114:117]
	v_mfma_i32_16x16x64_i8 v[114:117], v[190:193], v[198:201], v[114:117]
	s_setprio 0
	s_barrier
	s_add_i32 s20, s51, s33
	v_lshl_add_u64 v[162:163], v[162:163], 0, s[30:31]
	s_mov_b32 m0, s20
	ds_read_b128 v[194:197], v184 offset:49152
	ds_read_b128 v[198:201], v184 offset:50176
	ds_read_b128 v[202:205], v184 offset:51200
	ds_read_b128 v[206:209], v184 offset:52224
	ds_read_b128 v[224:227], v184 offset:53248
	ds_read_b128 v[228:231], v184 offset:54272
	ds_read_b128 v[232:235], v184 offset:55296
	ds_read_b128 v[236:239], v184 offset:56320
	global_load_lds_dwordx4 v[162:163], off
	s_add_i32 m0, s20, 0x2000
	s_add_u32 s16, s16, 0x40080
	v_lshl_add_u64 v[162:163], v[164:165], 0, s[30:31]
	s_addc_u32 s17, s17, 0
	s_add_i32 s20, s52, s33
	global_load_lds_dwordx4 v[162:163], off
	s_mov_b32 m0, s20
	s_nop 0
	global_load_lds_dwordx4 v0, s[16:17]
	s_add_i32 m0, s20, 0x2000
	s_nop 0
	global_load_lds_dwordx4 v138, s[16:17]
	v_lshl_add_u64 v[162:163], v[166:167], 0, s[30:31]
	s_mov_b32 m0, s34
	s_nop 0
	global_load_lds_dwordx4 v[162:163], off
	v_lshl_add_u64 v[162:163], v[168:169], 0, s[30:31]
	s_mov_b32 m0, s35
	s_nop 0
	global_load_lds_dwordx4 v[162:163], off
	s_waitcnt vmcnt(8)
	s_waitcnt lgkmcnt(0)
	s_barrier
	s_setprio 1
	s_waitcnt lgkmcnt(0)
	v_mfma_i32_16x16x64_i8 v[50:53], v[186:189], v[194:197], v[50:53]
	v_mfma_i32_16x16x64_i8 v[50:53], v[190:193], v[198:201], v[50:53]
	v_mfma_i32_16x16x64_i8 v[34:37], v[186:189], v[202:205], v[34:37]
	v_mfma_i32_16x16x64_i8 v[34:37], v[190:193], v[206:209], v[34:37]
	v_mfma_i32_16x16x64_i8 v[18:21], v[186:189], v[224:227], v[18:21]
	v_mfma_i32_16x16x64_i8 v[18:21], v[190:193], v[228:231], v[18:21]
	v_mfma_i32_16x16x64_i8 v[2:5], v[186:189], v[232:235], v[2:5]
	v_mfma_i32_16x16x64_i8 v[2:5], v[190:193], v[236:239], v[2:5]
	v_mfma_i32_16x16x64_i8 v[10:13], v[158:161], v[232:235], v[10:13]
	v_mfma_i32_16x16x64_i8 v[10:13], v[174:177], v[236:239], v[10:13]
	v_mfma_i32_16x16x64_i8 v[26:29], v[158:161], v[224:227], v[26:29]
	v_mfma_i32_16x16x64_i8 v[26:29], v[174:177], v[228:231], v[26:29]
	v_mfma_i32_16x16x64_i8 v[42:45], v[158:161], v[202:205], v[42:45]
	v_mfma_i32_16x16x64_i8 v[42:45], v[174:177], v[206:209], v[42:45]
	v_mfma_i32_16x16x64_i8 v[58:61], v[158:161], v[194:197], v[58:61]
	v_mfma_i32_16x16x64_i8 v[58:61], v[174:177], v[198:201], v[58:61]
	v_mfma_i32_16x16x64_i8 v[54:57], v[150:153], v[194:197], v[54:57]
	v_mfma_i32_16x16x64_i8 v[54:57], v[154:157], v[198:201], v[54:57]
	v_mfma_i32_16x16x64_i8 v[38:41], v[150:153], v[202:205], v[38:41]
	v_mfma_i32_16x16x64_i8 v[38:41], v[154:157], v[206:209], v[38:41]
	v_mfma_i32_16x16x64_i8 v[22:25], v[150:153], v[224:227], v[22:25]
	v_mfma_i32_16x16x64_i8 v[22:25], v[154:157], v[228:231], v[22:25]
	v_mfma_i32_16x16x64_i8 v[6:9], v[150:153], v[232:235], v[6:9]
	v_mfma_i32_16x16x64_i8 v[6:9], v[154:157], v[236:239], v[6:9]
	v_mfma_i32_16x16x64_i8 v[14:17], v[130:133], v[232:235], v[14:17]
	v_mfma_i32_16x16x64_i8 v[14:17], v[134:137], v[236:239], v[14:17]
	v_mfma_i32_16x16x64_i8 v[30:33], v[130:133], v[224:227], v[30:33]
	v_mfma_i32_16x16x64_i8 v[30:33], v[134:137], v[228:231], v[30:33]
	v_mfma_i32_16x16x64_i8 v[46:49], v[130:133], v[202:205], v[46:49]
	v_mfma_i32_16x16x64_i8 v[46:49], v[134:137], v[206:209], v[46:49]
	v_mfma_i32_16x16x64_i8 v[62:65], v[130:133], v[194:197], v[62:65]
	v_mfma_i32_16x16x64_i8 v[62:65], v[134:137], v[198:201], v[62:65]
	s_setprio 0
	s_barrier
	s_add_i32 s50, s50, 2
	s_add_u32 s14, s14, 0x100
	s_addc_u32 s15, s15, 0
	s_add_u32 s48, s48, 0x100
	s_addc_u32 s49, s49, 0
	s_cmp_gt_u32 s50, 13
	s_cbranch_scc0 .LBB0_411
	v_readlane_b32 s14, v253, 2
	v_readlane_b32 s15, v253, 3
	s_and_b64 vcc, exec, s[14:15]
	s_cbranch_vccz .LBB0_414
	s_barrier

.LBB0_493:
	s_add_u32 s16, s12, 0x100
	s_addc_u32 s17, s13, 0
	s_add_i32 s67, 0, 0x10000
	s_cmpk_eq_i32 s19, 0x54
	s_cselect_b32 s23, s7, s17
	s_cselect_b32 s22, s6, s16
	s_cselect_b32 s21, s11, s18
	s_cselect_b32 s20, s10, s15
	s_add_i32 s68, 0, 0x14000
	v_add_u32_e32 v142, s67, v205
	v_add_u32_e32 v162, s68, v205
	ds_read_b128 v[130:133], v142
	ds_read_b128 v[134:137], v142 offset:1024
	ds_read_b128 v[138:141], v142 offset:2048
	ds_read_b128 v[142:145], v142 offset:3072
	ds_read_b128 v[146:149], v162
	ds_read_b128 v[150:153], v162 offset:1024
	ds_read_b128 v[154:157], v162 offset:2048
	ds_read_b128 v[184:187], v162 offset:3072
	s_add_i32 m0, s28, 0xc000
	ds_read_b128 v[188:191], v230
	ds_read_b128 v[192:195], v230 offset:1024
	ds_read_b128 v[196:199], v230 offset:2048
	ds_read_b128 v[200:203], v230 offset:3072
	ds_read_b128 v[232:235], v230 offset:4096
	ds_read_b128 v[236:239], v230 offset:5120
	ds_read_b128 v[240:243], v230 offset:6144
	ds_read_b128 v[244:247], v230 offset:7168
	global_load_lds_dwordx4 v180, s[12:13]
	s_add_i32 m0, s28, 0xe000
	s_nop 0
	global_load_lds_dwordx4 v182, s[12:13]
	s_waitcnt vmcnt(8)
	s_waitcnt lgkmcnt(0)
	s_barrier
	s_setprio 1
	s_waitcnt lgkmcnt(0)
	v_mfma_f32_16x16x32_bf16 v[126:129], v[130:133], v[188:191], v[126:129]
	v_mfma_f32_16x16x32_bf16 v[126:129], v[134:137], v[192:195], v[126:129]
	v_mfma_f32_16x16x32_bf16 v[118:121], v[130:133], v[196:199], v[118:121]
	v_mfma_f32_16x16x32_bf16 v[118:121], v[134:137], v[200:203], v[118:121]
	v_mfma_f32_16x16x32_bf16 v[110:113], v[130:133], v[232:235], v[110:113]
	v_mfma_f32_16x16x32_bf16 v[110:113], v[134:137], v[236:239], v[110:113]
	v_mfma_f32_16x16x32_bf16 v[102:105], v[130:133], v[240:243], v[102:105]
	v_mfma_f32_16x16x32_bf16 v[102:105], v[134:137], v[244:247], v[102:105]
	v_mfma_f32_16x16x32_bf16 v[38:41], v[138:141], v[240:243], v[38:41]
	v_mfma_f32_16x16x32_bf16 v[38:41], v[142:145], v[244:247], v[38:41]
	v_mfma_f32_16x16x32_bf16 v[66:69], v[138:141], v[232:235], v[66:69]
	v_mfma_f32_16x16x32_bf16 v[66:69], v[142:145], v[236:239], v[66:69]
	v_mfma_f32_16x16x32_bf16 v[86:89], v[138:141], v[196:199], v[86:89]
	v_mfma_f32_16x16x32_bf16 v[86:89], v[142:145], v[200:203], v[86:89]
	v_mfma_f32_16x16x32_bf16 v[74:77], v[138:141], v[188:191], v[74:77]
	v_mfma_f32_16x16x32_bf16 v[74:77], v[142:145], v[192:195], v[74:77]
	v_mfma_f32_16x16x32_bf16 v[122:125], v[146:149], v[188:191], v[122:125]
	v_mfma_f32_16x16x32_bf16 v[122:125], v[150:153], v[192:195], v[122:125]
	v_mfma_f32_16x16x32_bf16 v[114:117], v[146:149], v[196:199], v[114:117]
	v_mfma_f32_16x16x32_bf16 v[114:117], v[150:153], v[200:203], v[114:117]
	v_mfma_f32_16x16x32_bf16 v[106:109], v[146:149], v[232:235], v[106:109]
	v_mfma_f32_16x16x32_bf16 v[106:109], v[150:153], v[236:239], v[106:109]
	v_mfma_f32_16x16x32_bf16 v[98:101], v[146:149], v[240:243], v[98:101]
	v_mfma_f32_16x16x32_bf16 v[98:101], v[150:153], v[244:247], v[98:101]
	v_mfma_f32_16x16x32_bf16 v[42:45], v[154:157], v[240:243], v[42:45]
	v_mfma_f32_16x16x32_bf16 v[42:45], v[184:187], v[244:247], v[42:45]
	v_mfma_f32_16x16x32_bf16 v[70:73], v[154:157], v[232:235], v[70:73]
	v_mfma_f32_16x16x32_bf16 v[70:73], v[184:187], v[236:239], v[70:73]
	v_mfma_f32_16x16x32_bf16 v[90:93], v[154:157], v[196:199], v[90:93]
	v_mfma_f32_16x16x32_bf16 v[90:93], v[184:187], v[200:203], v[90:93]
	v_mfma_f32_16x16x32_bf16 v[82:85], v[154:157], v[188:191], v[82:85]
	v_mfma_f32_16x16x32_bf16 v[82:85], v[184:187], v[192:195], v[82:85]
	s_setprio 0
	s_barrier
	s_add_i32 s12, s67, s33
	v_lshl_add_u64 v[162:163], s[20:21], 0, v[0:1]
	s_mov_b32 m0, s12
	ds_read_b128 v[188:191], v230 offset:16384
	ds_read_b128 v[192:195], v230 offset:17408
	ds_read_b128 v[196:199], v230 offset:18432
	ds_read_b128 v[200:203], v230 offset:19456
	ds_read_b128 v[232:235], v230 offset:20480
	ds_read_b128 v[236:239], v230 offset:21504
	ds_read_b128 v[240:243], v230 offset:22528
	ds_read_b128 v[244:247], v230 offset:23552
	global_load_lds_dwordx4 v[162:163], off
	s_add_i32 m0, s12, 0x2000
	s_add_u32 s12, s20, 0x160000
	v_lshl_add_u64 v[164:165], s[20:21], 0, v[158:159]
	s_addc_u32 s13, s21, 0
	s_add_i32 s67, s68, s33
	global_load_lds_dwordx4 v[164:165], off
	s_mov_b32 m0, s67
	v_lshl_add_u64 v[168:169], s[22:23], 0, v[160:161]
	global_load_lds_dwordx4 v0, s[12:13]
	s_add_i32 m0, s67, 0x2000
	s_nop 0
	global_load_lds_dwordx4 v158, s[12:13]
	v_lshl_add_u64 v[166:167], s[22:23], 0, v[174:175]
	s_mov_b32 m0, s28
	s_nop 0
	global_load_lds_dwordx4 v[166:167], off
	s_mov_b32 m0, s29
	s_nop 0
	global_load_lds_dwordx4 v[168:169], off
	s_waitcnt vmcnt(8)
	s_waitcnt lgkmcnt(0)
	s_barrier
	s_setprio 1
	s_waitcnt lgkmcnt(0)
	v_mfma_f32_16x16x32_bf16 v[58:61], v[154:157], v[188:191], v[58:61]
	v_mfma_f32_16x16x32_bf16 v[58:61], v[184:187], v[192:195], v[58:61]
	v_mfma_f32_16x16x32_bf16 v[34:37], v[154:157], v[196:199], v[34:37]
	v_mfma_f32_16x16x32_bf16 v[34:37], v[184:187], v[200:203], v[34:37]
	v_mfma_f32_16x16x32_bf16 v[14:17], v[154:157], v[232:235], v[14:17]
	v_mfma_f32_16x16x32_bf16 v[14:17], v[184:187], v[236:239], v[14:17]
	v_mfma_f32_16x16x32_bf16 v[6:9], v[154:157], v[240:243], v[6:9]
	v_mfma_f32_16x16x32_bf16 v[6:9], v[184:187], v[244:247], v[6:9]
	v_mfma_f32_16x16x32_bf16 v[18:21], v[146:149], v[240:243], v[18:21]
	v_mfma_f32_16x16x32_bf16 v[18:21], v[150:153], v[244:247], v[18:21]
	v_mfma_f32_16x16x32_bf16 v[26:29], v[146:149], v[232:235], v[26:29]
	v_mfma_f32_16x16x32_bf16 v[26:29], v[150:153], v[236:239], v[26:29]
	v_mfma_f32_16x16x32_bf16 v[54:57], v[146:149], v[196:199], v[54:57]
	v_mfma_f32_16x16x32_bf16 v[54:57], v[150:153], v[200:203], v[54:57]
	v_mfma_f32_16x16x32_bf16 v[78:81], v[146:149], v[188:191], v[78:81]
	v_mfma_f32_16x16x32_bf16 v[78:81], v[150:153], v[192:195], v[78:81]
	v_mfma_f32_16x16x32_bf16 v[50:53], v[138:141], v[188:191], v[50:53]
	v_mfma_f32_16x16x32_bf16 v[50:53], v[142:145], v[192:195], v[50:53]
	v_mfma_f32_16x16x32_bf16 v[30:33], v[138:141], v[196:199], v[30:33]
	v_mfma_f32_16x16x32_bf16 v[30:33], v[142:145], v[200:203], v[30:33]
	v_mfma_f32_16x16x32_bf16 v[10:13], v[138:141], v[232:235], v[10:13]
	v_mfma_f32_16x16x32_bf16 v[10:13], v[142:145], v[236:239], v[10:13]
	v_mfma_f32_16x16x32_bf16 v[2:5], v[138:141], v[240:243], v[2:5]
	v_mfma_f32_16x16x32_bf16 v[2:5], v[142:145], v[244:247], v[2:5]
	v_mfma_f32_16x16x32_bf16 v[22:25], v[130:133], v[240:243], v[22:25]
	v_mfma_f32_16x16x32_bf16 v[22:25], v[134:137], v[244:247], v[22:25]
	v_mfma_f32_16x16x32_bf16 v[46:49], v[130:133], v[232:235], v[46:49]
	v_mfma_f32_16x16x32_bf16 v[46:49], v[134:137], v[236:239], v[46:49]
	v_mfma_f32_16x16x32_bf16 v[62:65], v[130:133], v[196:199], v[62:65]
	v_mfma_f32_16x16x32_bf16 v[62:65], v[134:137], v[200:203], v[62:65]
	v_mfma_f32_16x16x32_bf16 v[94:97], v[130:133], v[188:191], v[94:97]
	v_mfma_f32_16x16x32_bf16 v[94:97], v[134:137], v[192:195], v[94:97]
	s_setprio 0
	s_barrier
	s_add_i32 s67, 0, 0x18000
	s_add_i32 s68, 0, 0x1c000
	v_add_u32_e32 v142, s67, v205
	v_add_u32_e32 v170, s68, v205
	ds_read_b128 v[130:133], v142
	ds_read_b128 v[134:137], v142 offset:1024
	ds_read_b128 v[138:141], v142 offset:2048
	ds_read_b128 v[142:145], v142 offset:3072
	ds_read_b128 v[146:149], v170
	ds_read_b128 v[150:153], v170 offset:1024
	ds_read_b128 v[154:157], v170 offset:2048
	ds_read_b128 v[184:187], v170 offset:3072
	s_add_u32 s12, s22, 0x160000
	s_addc_u32 s13, s23, 0
	s_mov_b32 m0, s34
	ds_read_b128 v[188:191], v230 offset:32768
	ds_read_b128 v[192:195], v230 offset:33792
	ds_read_b128 v[196:199], v230 offset:34816
	ds_read_b128 v[200:203], v230 offset:35840
	ds_read_b128 v[232:235], v230 offset:36864
	ds_read_b128 v[236:239], v230 offset:37888
	ds_read_b128 v[240:243], v230 offset:38912
	ds_read_b128 v[244:247], v230 offset:39936
	global_load_lds_dwordx4 v174, s[12:13]
	s_mov_b32 m0, s35
	s_nop 0
	global_load_lds_dwordx4 v160, s[12:13]
	s_waitcnt vmcnt(8)
	s_waitcnt lgkmcnt(0)
	s_barrier
	s_setprio 1
	s_waitcnt lgkmcnt(0)
	v_mfma_f32_16x16x32_bf16 v[126:129], v[130:133], v[188:191], v[126:129]
	v_mfma_f32_16x16x32_bf16 v[126:129], v[134:137], v[192:195], v[126:129]
	v_mfma_f32_16x16x32_bf16 v[118:121], v[130:133], v[196:199], v[118:121]
	v_mfma_f32_16x16x32_bf16 v[118:121], v[134:137], v[200:203], v[118:121]
	v_mfma_f32_16x16x32_bf16 v[110:113], v[130:133], v[232:235], v[110:113]
	v_mfma_f32_16x16x32_bf16 v[110:113], v[134:137], v[236:239], v[110:113]
	v_mfma_f32_16x16x32_bf16 v[102:105], v[130:133], v[240:243], v[102:105]
	v_mfma_f32_16x16x32_bf16 v[102:105], v[134:137], v[244:247], v[102:105]
	v_mfma_f32_16x16x32_bf16 v[38:41], v[138:141], v[240:243], v[38:41]
	v_mfma_f32_16x16x32_bf16 v[38:41], v[142:145], v[244:247], v[38:41]
	v_mfma_f32_16x16x32_bf16 v[66:69], v[138:141], v[232:235], v[66:69]
	v_mfma_f32_16x16x32_bf16 v[66:69], v[142:145], v[236:239], v[66:69]
	v_mfma_f32_16x16x32_bf16 v[86:89], v[138:141], v[196:199], v[86:89]
	v_mfma_f32_16x16x32_bf16 v[86:89], v[142:145], v[200:203], v[86:89]
	v_mfma_f32_16x16x32_bf16 v[74:77], v[138:141], v[188:191], v[74:77]
	v_mfma_f32_16x16x32_bf16 v[74:77], v[142:145], v[192:195], v[74:77]
	v_mfma_f32_16x16x32_bf16 v[122:125], v[146:149], v[188:191], v[122:125]
	v_mfma_f32_16x16x32_bf16 v[122:125], v[150:153], v[192:195], v[122:125]
	v_mfma_f32_16x16x32_bf16 v[114:117], v[146:149], v[196:199], v[114:117]
	v_mfma_f32_16x16x32_bf16 v[114:117], v[150:153], v[200:203], v[114:117]
	v_mfma_f32_16x16x32_bf16 v[106:109], v[146:149], v[232:235], v[106:109]
	v_mfma_f32_16x16x32_bf16 v[106:109], v[150:153], v[236:239], v[106:109]
	v_mfma_f32_16x16x32_bf16 v[98:101], v[146:149], v[240:243], v[98:101]
	v_mfma_f32_16x16x32_bf16 v[98:101], v[150:153], v[244:247], v[98:101]
	v_mfma_f32_16x16x32_bf16 v[42:45], v[154:157], v[240:243], v[42:45]
	v_mfma_f32_16x16x32_bf16 v[42:45], v[184:187], v[244:247], v[42:45]
	v_mfma_f32_16x16x32_bf16 v[70:73], v[154:157], v[232:235], v[70:73]
	v_mfma_f32_16x16x32_bf16 v[70:73], v[184:187], v[236:239], v[70:73]
	v_mfma_f32_16x16x32_bf16 v[90:93], v[154:157], v[196:199], v[90:93]
	v_mfma_f32_16x16x32_bf16 v[90:93], v[184:187], v[200:203], v[90:93]
	v_mfma_f32_16x16x32_bf16 v[82:85], v[154:157], v[188:191], v[82:85]
	v_mfma_f32_16x16x32_bf16 v[82:85], v[184:187], v[192:195], v[82:85]
	s_setprio 0
	s_barrier
	s_add_i32 s12, s67, s33
	v_lshl_add_u64 v[162:163], v[162:163], 0, s[30:31]
	s_mov_b32 m0, s12
	ds_read_b128 v[188:191], v230 offset:49152
	ds_read_b128 v[192:195], v230 offset:50176
	ds_read_b128 v[196:199], v230 offset:51200
	ds_read_b128 v[200:203], v230 offset:52224
	ds_read_b128 v[232:235], v230 offset:53248
	ds_read_b128 v[236:239], v230 offset:54272
	ds_read_b128 v[240:243], v230 offset:55296
	ds_read_b128 v[244:247], v230 offset:56320
	global_load_lds_dwordx4 v[162:163], off
	s_add_i32 m0, s12, 0x2000
	s_add_u32 s12, s20, 0x160080
	v_lshl_add_u64 v[162:163], v[164:165], 0, s[30:31]
	s_addc_u32 s13, s21, 0
	s_add_i32 s20, s68, s33
	global_load_lds_dwordx4 v[162:163], off
	s_mov_b32 m0, s20
	s_nop 0
	global_load_lds_dwordx4 v0, s[12:13]
	s_add_i32 m0, s20, 0x2000
	s_nop 0
	global_load_lds_dwordx4 v158, s[12:13]
	v_lshl_add_u64 v[162:163], v[166:167], 0, s[30:31]
	s_mov_b32 m0, s55
	s_nop 0
	global_load_lds_dwordx4 v[162:163], off
	v_lshl_add_u64 v[162:163], v[168:169], 0, s[30:31]
	s_mov_b32 m0, s56
	s_nop 0
	global_load_lds_dwordx4 v[162:163], off
	s_waitcnt vmcnt(8)
	s_waitcnt lgkmcnt(0)
	s_barrier
	s_setprio 1
	s_waitcnt lgkmcnt(0)
	v_mfma_f32_16x16x32_bf16 v[58:61], v[154:157], v[188:191], v[58:61]
	v_mfma_f32_16x16x32_bf16 v[58:61], v[184:187], v[192:195], v[58:61]
	v_mfma_f32_16x16x32_bf16 v[34:37], v[154:157], v[196:199], v[34:37]
	v_mfma_f32_16x16x32_bf16 v[34:37], v[184:187], v[200:203], v[34:37]
	v_mfma_f32_16x16x32_bf16 v[14:17], v[154:157], v[232:235], v[14:17]
	v_mfma_f32_16x16x32_bf16 v[14:17], v[184:187], v[236:239], v[14:17]
	v_mfma_f32_16x16x32_bf16 v[6:9], v[154:157], v[240:243], v[6:9]
	v_mfma_f32_16x16x32_bf16 v[6:9], v[184:187], v[244:247], v[6:9]
	v_mfma_f32_16x16x32_bf16 v[18:21], v[146:149], v[240:243], v[18:21]
	v_mfma_f32_16x16x32_bf16 v[18:21], v[150:153], v[244:247], v[18:21]
	v_mfma_f32_16x16x32_bf16 v[26:29], v[146:149], v[232:235], v[26:29]
	v_mfma_f32_16x16x32_bf16 v[26:29], v[150:153], v[236:239], v[26:29]
	v_mfma_f32_16x16x32_bf16 v[54:57], v[146:149], v[196:199], v[54:57]
	v_mfma_f32_16x16x32_bf16 v[54:57], v[150:153], v[200:203], v[54:57]
	v_mfma_f32_16x16x32_bf16 v[78:81], v[146:149], v[188:191], v[78:81]
	v_mfma_f32_16x16x32_bf16 v[78:81], v[150:153], v[192:195], v[78:81]
	v_mfma_f32_16x16x32_bf16 v[50:53], v[138:141], v[188:191], v[50:53]
	v_mfma_f32_16x16x32_bf16 v[50:53], v[142:145], v[192:195], v[50:53]
	v_mfma_f32_16x16x32_bf16 v[30:33], v[138:141], v[196:199], v[30:33]
	v_mfma_f32_16x16x32_bf16 v[30:33], v[142:145], v[200:203], v[30:33]
	v_mfma_f32_16x16x32_bf16 v[10:13], v[138:141], v[232:235], v[10:13]
	v_mfma_f32_16x16x32_bf16 v[10:13], v[142:145], v[236:239], v[10:13]
	v_mfma_f32_16x16x32_bf16 v[2:5], v[138:141], v[240:243], v[2:5]
	v_mfma_f32_16x16x32_bf16 v[2:5], v[142:145], v[244:247], v[2:5]
	v_mfma_f32_16x16x32_bf16 v[22:25], v[130:133], v[240:243], v[22:25]
	v_mfma_f32_16x16x32_bf16 v[22:25], v[134:137], v[244:247], v[22:25]
	v_mfma_f32_16x16x32_bf16 v[46:49], v[130:133], v[232:235], v[46:49]
	v_mfma_f32_16x16x32_bf16 v[46:49], v[134:137], v[236:239], v[46:49]
	v_mfma_f32_16x16x32_bf16 v[62:65], v[130:133], v[196:199], v[62:65]
	v_mfma_f32_16x16x32_bf16 v[62:65], v[134:137], v[200:203], v[62:65]
	v_mfma_f32_16x16x32_bf16 v[94:97], v[130:133], v[188:191], v[94:97]
	v_mfma_f32_16x16x32_bf16 v[94:97], v[134:137], v[192:195], v[94:97]
	s_setprio 0
	s_barrier
	s_add_i32 s19, s19, 2
	s_add_u32 s15, s15, 0x100
	s_addc_u32 s18, s18, 0
	s_cmpk_gt_u32 s19, 0x55
	s_mov_b64 s[12:13], s[16:17]
	s_cbranch_scc0 .LBB0_493
	v_readlane_b32 s12, v253, 2
	v_readlane_b32 s13, v253, 3
	s_and_b64 vcc, exec, s[12:13]
	s_cbranch_vccz .LBB0_496
	s_barrier

.LBB0_641:
	s_add_u32 s28, s26, 0xfffc0080
	s_addc_u32 s29, s27, -1
	s_add_i32 s57, 0, 0x10000
	s_cmp_eq_u32 s56, 12
	s_cselect_b32 s43, s15, s29
	s_cselect_b32 s42, s19, s28
	s_cselect_b32 s29, s11, s55
	s_cselect_b32 s28, s53, s54
	s_add_i32 s60, 0, 0x14000
	v_add_u32_e32 v152, s57, v159
	v_add_u32_e32 v156, s60, v159
	ds_read_b128 v[140:143], v152
	ds_read_b128 v[144:147], v152 offset:1024
	ds_read_b128 v[148:151], v152 offset:2048
	ds_read_b128 v[152:155], v152 offset:3072
	ds_read_b128 v[176:179], v156
	ds_read_b128 v[180:183], v156 offset:1024
	ds_read_b128 v[184:187], v156 offset:2048
	ds_read_b128 v[188:191], v156 offset:3072
	s_add_i32 m0, s44, 0xc000
	ds_read_b128 v[192:195], v174
	ds_read_b128 v[196:199], v174 offset:1024
	ds_read_b128 v[200:203], v174 offset:2048
	ds_read_b128 v[204:207], v174 offset:3072
	ds_read_b128 v[208:211], v174 offset:4096
	ds_read_b128 v[224:227], v174 offset:5120
	ds_read_b128 v[228:231], v174 offset:6144
	ds_read_b128 v[232:235], v174 offset:7168
	global_load_lds_dwordx4 v136, s[26:27]
	s_add_i32 m0, s44, 0xe000
	s_nop 0
	global_load_lds_dwordx4 v138, s[26:27]
	s_waitcnt vmcnt(8)
	s_waitcnt lgkmcnt(0)
	s_barrier
	s_setprio 1
	s_waitcnt lgkmcnt(0)
	v_mfma_i32_16x16x64_i8 v[126:129], v[140:143], v[192:195], v[126:129]
	v_mfma_i32_16x16x64_i8 v[126:129], v[144:147], v[196:199], v[126:129]
	v_mfma_i32_16x16x64_i8 v[110:113], v[140:143], v[200:203], v[110:113]
	v_mfma_i32_16x16x64_i8 v[110:113], v[144:147], v[204:207], v[110:113]
	v_mfma_i32_16x16x64_i8 v[94:97], v[140:143], v[208:211], v[94:97]
	v_mfma_i32_16x16x64_i8 v[94:97], v[144:147], v[224:227], v[94:97]
	v_mfma_i32_16x16x64_i8 v[78:81], v[140:143], v[228:231], v[78:81]
	v_mfma_i32_16x16x64_i8 v[78:81], v[144:147], v[232:235], v[78:81]
	v_mfma_i32_16x16x64_i8 v[74:77], v[148:151], v[228:231], v[74:77]
	v_mfma_i32_16x16x64_i8 v[74:77], v[152:155], v[232:235], v[74:77]
	v_mfma_i32_16x16x64_i8 v[90:93], v[148:151], v[208:211], v[90:93]
	v_mfma_i32_16x16x64_i8 v[90:93], v[152:155], v[224:227], v[90:93]
	v_mfma_i32_16x16x64_i8 v[106:109], v[148:151], v[200:203], v[106:109]
	v_mfma_i32_16x16x64_i8 v[106:109], v[152:155], v[204:207], v[106:109]
	v_mfma_i32_16x16x64_i8 v[122:125], v[148:151], v[192:195], v[122:125]
	v_mfma_i32_16x16x64_i8 v[122:125], v[152:155], v[196:199], v[122:125]
	v_mfma_i32_16x16x64_i8 v[118:121], v[176:179], v[192:195], v[118:121]
	v_mfma_i32_16x16x64_i8 v[118:121], v[180:183], v[196:199], v[118:121]
	v_mfma_i32_16x16x64_i8 v[102:105], v[176:179], v[200:203], v[102:105]
	v_mfma_i32_16x16x64_i8 v[102:105], v[180:183], v[204:207], v[102:105]
	v_mfma_i32_16x16x64_i8 v[86:89], v[176:179], v[208:211], v[86:89]
	v_mfma_i32_16x16x64_i8 v[86:89], v[180:183], v[224:227], v[86:89]
	v_mfma_i32_16x16x64_i8 v[70:73], v[176:179], v[228:231], v[70:73]
	v_mfma_i32_16x16x64_i8 v[70:73], v[180:183], v[232:235], v[70:73]
	v_mfma_i32_16x16x64_i8 v[66:69], v[184:187], v[228:231], v[66:69]
	v_mfma_i32_16x16x64_i8 v[66:69], v[188:191], v[232:235], v[66:69]
	v_mfma_i32_16x16x64_i8 v[82:85], v[184:187], v[208:211], v[82:85]
	v_mfma_i32_16x16x64_i8 v[82:85], v[188:191], v[224:227], v[82:85]
	v_mfma_i32_16x16x64_i8 v[98:101], v[184:187], v[200:203], v[98:101]
	v_mfma_i32_16x16x64_i8 v[98:101], v[188:191], v[204:207], v[98:101]
	v_mfma_i32_16x16x64_i8 v[114:117], v[184:187], v[192:195], v[114:117]
	v_mfma_i32_16x16x64_i8 v[114:117], v[188:191], v[196:199], v[114:117]
	s_setprio 0
	s_barrier
	s_add_i32 s57, s57, s33
	v_lshl_add_u64 v[156:157], s[28:29], 0, v[0:1]
	s_mov_b32 m0, s57
	ds_read_b128 v[192:195], v174 offset:16384
	ds_read_b128 v[196:199], v174 offset:17408
	ds_read_b128 v[200:203], v174 offset:18432
	ds_read_b128 v[204:207], v174 offset:19456
	ds_read_b128 v[208:211], v174 offset:20480
	ds_read_b128 v[224:227], v174 offset:21504
	ds_read_b128 v[228:231], v174 offset:22528
	ds_read_b128 v[232:235], v174 offset:23552
	global_load_lds_dwordx4 v[156:157], off
	s_add_i32 m0, s57, 0x2000
	s_add_u32 s58, s28, 0x40000
	v_lshl_add_u64 v[162:163], s[28:29], 0, v[130:131]
	s_addc_u32 s59, s29, 0
	s_add_i32 s57, s60, s33
	global_load_lds_dwordx4 v[162:163], off
	s_mov_b32 m0, s57
	v_lshl_add_u64 v[166:167], s[42:43], 0, v[132:133]
	global_load_lds_dwordx4 v0, s[58:59]
	s_add_i32 m0, s57, 0x2000
	s_nop 0
	global_load_lds_dwordx4 v130, s[58:59]
	v_lshl_add_u64 v[164:165], s[42:43], 0, v[134:135]
	s_mov_b32 m0, s44
	s_nop 0
	global_load_lds_dwordx4 v[164:165], off
	s_mov_b32 m0, s45
	s_nop 0
	global_load_lds_dwordx4 v[166:167], off
	s_waitcnt vmcnt(8)
	s_waitcnt lgkmcnt(0)
	s_barrier
	s_setprio 1
	s_waitcnt lgkmcnt(0)
	v_mfma_i32_16x16x64_i8 v[50:53], v[184:187], v[192:195], v[50:53]
	v_mfma_i32_16x16x64_i8 v[50:53], v[188:191], v[196:199], v[50:53]
	v_mfma_i32_16x16x64_i8 v[34:37], v[184:187], v[200:203], v[34:37]
	v_mfma_i32_16x16x64_i8 v[34:37], v[188:191], v[204:207], v[34:37]
	v_mfma_i32_16x16x64_i8 v[18:21], v[184:187], v[208:211], v[18:21]
	v_mfma_i32_16x16x64_i8 v[18:21], v[188:191], v[224:227], v[18:21]
	v_mfma_i32_16x16x64_i8 v[2:5], v[184:187], v[228:231], v[2:5]
	v_mfma_i32_16x16x64_i8 v[2:5], v[188:191], v[232:235], v[2:5]
	v_mfma_i32_16x16x64_i8 v[6:9], v[176:179], v[228:231], v[6:9]
	v_mfma_i32_16x16x64_i8 v[6:9], v[180:183], v[232:235], v[6:9]
	v_mfma_i32_16x16x64_i8 v[22:25], v[176:179], v[208:211], v[22:25]
	v_mfma_i32_16x16x64_i8 v[22:25], v[180:183], v[224:227], v[22:25]
	v_mfma_i32_16x16x64_i8 v[38:41], v[176:179], v[200:203], v[38:41]
	v_mfma_i32_16x16x64_i8 v[38:41], v[180:183], v[204:207], v[38:41]
	v_mfma_i32_16x16x64_i8 v[54:57], v[176:179], v[192:195], v[54:57]
	v_mfma_i32_16x16x64_i8 v[54:57], v[180:183], v[196:199], v[54:57]
	v_mfma_i32_16x16x64_i8 v[58:61], v[148:151], v[192:195], v[58:61]
	v_mfma_i32_16x16x64_i8 v[58:61], v[152:155], v[196:199], v[58:61]
	v_mfma_i32_16x16x64_i8 v[42:45], v[148:151], v[200:203], v[42:45]
	v_mfma_i32_16x16x64_i8 v[42:45], v[152:155], v[204:207], v[42:45]
	v_mfma_i32_16x16x64_i8 v[26:29], v[148:151], v[208:211], v[26:29]
	v_mfma_i32_16x16x64_i8 v[26:29], v[152:155], v[224:227], v[26:29]
	v_mfma_i32_16x16x64_i8 v[10:13], v[148:151], v[228:231], v[10:13]
	v_mfma_i32_16x16x64_i8 v[10:13], v[152:155], v[232:235], v[10:13]
	v_mfma_i32_16x16x64_i8 v[14:17], v[140:143], v[228:231], v[14:17]
	v_mfma_i32_16x16x64_i8 v[14:17], v[144:147], v[232:235], v[14:17]
	v_mfma_i32_16x16x64_i8 v[30:33], v[140:143], v[208:211], v[30:33]
	v_mfma_i32_16x16x64_i8 v[30:33], v[144:147], v[224:227], v[30:33]
	v_mfma_i32_16x16x64_i8 v[46:49], v[140:143], v[200:203], v[46:49]
	v_mfma_i32_16x16x64_i8 v[46:49], v[144:147], v[204:207], v[46:49]
	v_mfma_i32_16x16x64_i8 v[62:65], v[140:143], v[192:195], v[62:65]
	v_mfma_i32_16x16x64_i8 v[62:65], v[144:147], v[196:199], v[62:65]
	s_setprio 0
	s_barrier
	s_add_i32 s57, 0, 0x18000
	s_add_i32 s58, 0, 0x1c000
	v_add_u32_e32 v152, s57, v159
	v_add_u32_e32 v168, s58, v159
	ds_read_b128 v[140:143], v152
	ds_read_b128 v[144:147], v152 offset:1024
	ds_read_b128 v[148:151], v152 offset:2048
	ds_read_b128 v[152:155], v152 offset:3072
	ds_read_b128 v[176:179], v168
	ds_read_b128 v[180:183], v168 offset:1024
	ds_read_b128 v[184:187], v168 offset:2048
	ds_read_b128 v[188:191], v168 offset:3072
	s_add_u32 s42, s42, 0x40000
	s_addc_u32 s43, s43, 0
	s_mov_b32 m0, s46
	ds_read_b128 v[192:195], v174 offset:32768
	ds_read_b128 v[196:199], v174 offset:33792
	ds_read_b128 v[200:203], v174 offset:34816
	ds_read_b128 v[204:207], v174 offset:35840
	ds_read_b128 v[208:211], v174 offset:36864
	ds_read_b128 v[224:227], v174 offset:37888
	ds_read_b128 v[228:231], v174 offset:38912
	ds_read_b128 v[232:235], v174 offset:39936
	global_load_lds_dwordx4 v134, s[42:43]
	s_mov_b32 m0, s47
	s_nop 0
	global_load_lds_dwordx4 v132, s[42:43]
	s_waitcnt vmcnt(8)
	s_waitcnt lgkmcnt(0)
	s_barrier
	s_setprio 1
	s_waitcnt lgkmcnt(0)
	v_mfma_i32_16x16x64_i8 v[126:129], v[140:143], v[192:195], v[126:129]
	v_mfma_i32_16x16x64_i8 v[126:129], v[144:147], v[196:199], v[126:129]
	v_mfma_i32_16x16x64_i8 v[110:113], v[140:143], v[200:203], v[110:113]
	v_mfma_i32_16x16x64_i8 v[110:113], v[144:147], v[204:207], v[110:113]
	v_mfma_i32_16x16x64_i8 v[94:97], v[140:143], v[208:211], v[94:97]
	v_mfma_i32_16x16x64_i8 v[94:97], v[144:147], v[224:227], v[94:97]
	v_mfma_i32_16x16x64_i8 v[78:81], v[140:143], v[228:231], v[78:81]
	v_mfma_i32_16x16x64_i8 v[78:81], v[144:147], v[232:235], v[78:81]
	v_mfma_i32_16x16x64_i8 v[74:77], v[148:151], v[228:231], v[74:77]
	v_mfma_i32_16x16x64_i8 v[74:77], v[152:155], v[232:235], v[74:77]
	v_mfma_i32_16x16x64_i8 v[90:93], v[148:151], v[208:211], v[90:93]
	v_mfma_i32_16x16x64_i8 v[90:93], v[152:155], v[224:227], v[90:93]
	v_mfma_i32_16x16x64_i8 v[106:109], v[148:151], v[200:203], v[106:109]
	v_mfma_i32_16x16x64_i8 v[106:109], v[152:155], v[204:207], v[106:109]
	v_mfma_i32_16x16x64_i8 v[122:125], v[148:151], v[192:195], v[122:125]
	v_mfma_i32_16x16x64_i8 v[122:125], v[152:155], v[196:199], v[122:125]
	v_mfma_i32_16x16x64_i8 v[118:121], v[176:179], v[192:195], v[118:121]
	v_mfma_i32_16x16x64_i8 v[118:121], v[180:183], v[196:199], v[118:121]
	v_mfma_i32_16x16x64_i8 v[102:105], v[176:179], v[200:203], v[102:105]
	v_mfma_i32_16x16x64_i8 v[102:105], v[180:183], v[204:207], v[102:105]
	v_mfma_i32_16x16x64_i8 v[86:89], v[176:179], v[208:211], v[86:89]
	v_mfma_i32_16x16x64_i8 v[86:89], v[180:183], v[224:227], v[86:89]
	v_mfma_i32_16x16x64_i8 v[70:73], v[176:179], v[228:231], v[70:73]
	v_mfma_i32_16x16x64_i8 v[70:73], v[180:183], v[232:235], v[70:73]
	v_mfma_i32_16x16x64_i8 v[66:69], v[184:187], v[228:231], v[66:69]
	v_mfma_i32_16x16x64_i8 v[66:69], v[188:191], v[232:235], v[66:69]
	v_mfma_i32_16x16x64_i8 v[82:85], v[184:187], v[208:211], v[82:85]
	v_mfma_i32_16x16x64_i8 v[82:85], v[188:191], v[224:227], v[82:85]
	v_mfma_i32_16x16x64_i8 v[98:101], v[184:187], v[200:203], v[98:101]
	v_mfma_i32_16x16x64_i8 v[98:101], v[188:191], v[204:207], v[98:101]
	v_mfma_i32_16x16x64_i8 v[114:117], v[184:187], v[192:195], v[114:117]
	v_mfma_i32_16x16x64_i8 v[114:117], v[188:191], v[196:199], v[114:117]
	s_setprio 0
	s_barrier
	s_add_i32 s42, s57, s33
	v_lshl_add_u64 v[156:157], v[156:157], 0, s[30:31]
	s_mov_b32 m0, s42
	ds_read_b128 v[192:195], v174 offset:49152
	ds_read_b128 v[196:199], v174 offset:50176
	ds_read_b128 v[200:203], v174 offset:51200
	ds_read_b128 v[204:207], v174 offset:52224
	ds_read_b128 v[208:211], v174 offset:53248
	ds_read_b128 v[224:227], v174 offset:54272
	ds_read_b128 v[228:231], v174 offset:55296
	ds_read_b128 v[232:235], v174 offset:56320
	global_load_lds_dwordx4 v[156:157], off
	s_add_i32 m0, s42, 0x2000
	s_add_u32 s28, s28, 0x40080
	v_lshl_add_u64 v[156:157], v[162:163], 0, s[30:31]
	s_addc_u32 s29, s29, 0
	s_add_i32 s42, s58, s33
	global_load_lds_dwordx4 v[156:157], off
	s_mov_b32 m0, s42
	s_nop 0
	global_load_lds_dwordx4 v0, s[28:29]
	s_add_i32 m0, s42, 0x2000
	s_nop 0
	global_load_lds_dwordx4 v130, s[28:29]
	v_lshl_add_u64 v[156:157], v[164:165], 0, s[30:31]
	s_mov_b32 m0, s48
	s_nop 0
	global_load_lds_dwordx4 v[156:157], off
	v_lshl_add_u64 v[156:157], v[166:167], 0, s[30:31]
	s_mov_b32 m0, s49
	s_nop 0
	global_load_lds_dwordx4 v[156:157], off
	s_waitcnt vmcnt(8)
	s_waitcnt lgkmcnt(0)
	s_barrier
	s_setprio 1
	s_waitcnt lgkmcnt(0)
	v_mfma_i32_16x16x64_i8 v[50:53], v[184:187], v[192:195], v[50:53]
	v_mfma_i32_16x16x64_i8 v[50:53], v[188:191], v[196:199], v[50:53]
	v_mfma_i32_16x16x64_i8 v[34:37], v[184:187], v[200:203], v[34:37]
	v_mfma_i32_16x16x64_i8 v[34:37], v[188:191], v[204:207], v[34:37]
	v_mfma_i32_16x16x64_i8 v[18:21], v[184:187], v[208:211], v[18:21]
	v_mfma_i32_16x16x64_i8 v[18:21], v[188:191], v[224:227], v[18:21]
	v_mfma_i32_16x16x64_i8 v[2:5], v[184:187], v[228:231], v[2:5]
	v_mfma_i32_16x16x64_i8 v[2:5], v[188:191], v[232:235], v[2:5]
	v_mfma_i32_16x16x64_i8 v[6:9], v[176:179], v[228:231], v[6:9]
	v_mfma_i32_16x16x64_i8 v[6:9], v[180:183], v[232:235], v[6:9]
	v_mfma_i32_16x16x64_i8 v[22:25], v[176:179], v[208:211], v[22:25]
	v_mfma_i32_16x16x64_i8 v[22:25], v[180:183], v[224:227], v[22:25]
	v_mfma_i32_16x16x64_i8 v[38:41], v[176:179], v[200:203], v[38:41]
	v_mfma_i32_16x16x64_i8 v[38:41], v[180:183], v[204:207], v[38:41]
	v_mfma_i32_16x16x64_i8 v[54:57], v[176:179], v[192:195], v[54:57]
	v_mfma_i32_16x16x64_i8 v[54:57], v[180:183], v[196:199], v[54:57]
	v_mfma_i32_16x16x64_i8 v[58:61], v[148:151], v[192:195], v[58:61]
	v_mfma_i32_16x16x64_i8 v[58:61], v[152:155], v[196:199], v[58:61]
	v_mfma_i32_16x16x64_i8 v[42:45], v[148:151], v[200:203], v[42:45]
	v_mfma_i32_16x16x64_i8 v[42:45], v[152:155], v[204:207], v[42:45]
	v_mfma_i32_16x16x64_i8 v[26:29], v[148:151], v[208:211], v[26:29]
	v_mfma_i32_16x16x64_i8 v[26:29], v[152:155], v[224:227], v[26:29]
	v_mfma_i32_16x16x64_i8 v[10:13], v[148:151], v[228:231], v[10:13]
	v_mfma_i32_16x16x64_i8 v[10:13], v[152:155], v[232:235], v[10:13]
	v_mfma_i32_16x16x64_i8 v[14:17], v[140:143], v[228:231], v[14:17]
	v_mfma_i32_16x16x64_i8 v[14:17], v[144:147], v[232:235], v[14:17]
	v_mfma_i32_16x16x64_i8 v[30:33], v[140:143], v[208:211], v[30:33]
	v_mfma_i32_16x16x64_i8 v[30:33], v[144:147], v[224:227], v[30:33]
	v_mfma_i32_16x16x64_i8 v[46:49], v[140:143], v[200:203], v[46:49]
	v_mfma_i32_16x16x64_i8 v[46:49], v[144:147], v[204:207], v[46:49]
	v_mfma_i32_16x16x64_i8 v[62:65], v[140:143], v[192:195], v[62:65]
	v_mfma_i32_16x16x64_i8 v[62:65], v[144:147], v[196:199], v[62:65]
	s_setprio 0
	s_barrier
	s_add_i32 s56, s56, 2
	s_add_u32 s26, s26, 0x100
	s_addc_u32 s27, s27, 0
	s_add_u32 s54, s54, 0x100
	s_addc_u32 s55, s55, 0
	s_cmp_gt_u32 s56, 13
	s_cbranch_scc0 .LBB0_641
	v_readlane_b32 s26, v253, 2
	v_readlane_b32 s27, v253, 3
	s_and_b64 vcc, exec, s[26:27]
	s_cbranch_vccz .LBB0_644
	s_barrier

.LBB0_665:
	s_add_u32 s16, s6, 0xfff80080
	s_addc_u32 s17, s7, -1
	s_add_i32 s57, 0, 0x10000
	s_cmp_eq_u32 s56, 28
	s_cselect_b32 s21, s9, s17
	s_cselect_b32 s20, s18, s16
	s_cselect_b32 s17, s5, s55
	s_cselect_b32 s16, s19, s54
	s_add_i32 s60, 0, 0x14000
	v_add_u32_e32 v142, s57, v193
	v_add_u32_e32 v162, s60, v193
	ds_read_b128 v[130:133], v142
	ds_read_b128 v[134:137], v142 offset:1024
	ds_read_b128 v[138:141], v142 offset:2048
	ds_read_b128 v[142:145], v142 offset:3072
	ds_read_b128 v[158:161], v162
	ds_read_b128 v[174:177], v162 offset:1024
	ds_read_b128 v[178:181], v162 offset:2048
	ds_read_b128 v[182:185], v162 offset:3072
	s_add_i32 m0, s26, 0xc000
	ds_read_b128 v[186:189], v196
	ds_read_b128 v[198:201], v196 offset:1024
	ds_read_b128 v[202:205], v196 offset:2048
	ds_read_b128 v[206:209], v196 offset:3072
	ds_read_b128 v[224:227], v196 offset:4096
	ds_read_b128 v[228:231], v196 offset:5120
	ds_read_b128 v[232:235], v196 offset:6144
	ds_read_b128 v[236:239], v196 offset:7168
	global_load_lds_dwordx4 v154, s[6:7]
	s_add_i32 m0, s26, 0xe000
	s_nop 0
	global_load_lds_dwordx4 v156, s[6:7]
	s_waitcnt vmcnt(8)
	s_waitcnt lgkmcnt(0)
	s_barrier
	s_setprio 1
	s_waitcnt lgkmcnt(0)
	v_mfma_f32_16x16x32_bf16 v[126:129], v[130:133], v[186:189], v[126:129]
	v_mfma_f32_16x16x32_bf16 v[126:129], v[134:137], v[198:201], v[126:129]
	v_mfma_f32_16x16x32_bf16 v[110:113], v[130:133], v[202:205], v[110:113]
	v_mfma_f32_16x16x32_bf16 v[110:113], v[134:137], v[206:209], v[110:113]
	v_mfma_f32_16x16x32_bf16 v[94:97], v[130:133], v[224:227], v[94:97]
	v_mfma_f32_16x16x32_bf16 v[94:97], v[134:137], v[228:231], v[94:97]
	v_mfma_f32_16x16x32_bf16 v[78:81], v[130:133], v[232:235], v[78:81]
	v_mfma_f32_16x16x32_bf16 v[78:81], v[134:137], v[236:239], v[78:81]
	v_mfma_f32_16x16x32_bf16 v[74:77], v[138:141], v[232:235], v[74:77]
	v_mfma_f32_16x16x32_bf16 v[74:77], v[142:145], v[236:239], v[74:77]
	v_mfma_f32_16x16x32_bf16 v[90:93], v[138:141], v[224:227], v[90:93]
	v_mfma_f32_16x16x32_bf16 v[90:93], v[142:145], v[228:231], v[90:93]
	v_mfma_f32_16x16x32_bf16 v[106:109], v[138:141], v[202:205], v[106:109]
	v_mfma_f32_16x16x32_bf16 v[106:109], v[142:145], v[206:209], v[106:109]
	v_mfma_f32_16x16x32_bf16 v[122:125], v[138:141], v[186:189], v[122:125]
	v_mfma_f32_16x16x32_bf16 v[122:125], v[142:145], v[198:201], v[122:125]
	v_mfma_f32_16x16x32_bf16 v[118:121], v[158:161], v[186:189], v[118:121]
	v_mfma_f32_16x16x32_bf16 v[118:121], v[174:177], v[198:201], v[118:121]
	v_mfma_f32_16x16x32_bf16 v[102:105], v[158:161], v[202:205], v[102:105]
	v_mfma_f32_16x16x32_bf16 v[102:105], v[174:177], v[206:209], v[102:105]
	v_mfma_f32_16x16x32_bf16 v[86:89], v[158:161], v[224:227], v[86:89]
	v_mfma_f32_16x16x32_bf16 v[86:89], v[174:177], v[228:231], v[86:89]
	v_mfma_f32_16x16x32_bf16 v[70:73], v[158:161], v[232:235], v[70:73]
	v_mfma_f32_16x16x32_bf16 v[70:73], v[174:177], v[236:239], v[70:73]
	v_mfma_f32_16x16x32_bf16 v[66:69], v[178:181], v[232:235], v[66:69]
	v_mfma_f32_16x16x32_bf16 v[66:69], v[182:185], v[236:239], v[66:69]
	v_mfma_f32_16x16x32_bf16 v[82:85], v[178:181], v[224:227], v[82:85]
	v_mfma_f32_16x16x32_bf16 v[82:85], v[182:185], v[228:231], v[82:85]
	v_mfma_f32_16x16x32_bf16 v[98:101], v[178:181], v[202:205], v[98:101]
	v_mfma_f32_16x16x32_bf16 v[98:101], v[182:185], v[206:209], v[98:101]
	v_mfma_f32_16x16x32_bf16 v[114:117], v[178:181], v[186:189], v[114:117]
	v_mfma_f32_16x16x32_bf16 v[114:117], v[182:185], v[198:201], v[114:117]
	s_setprio 0
	s_barrier
	s_add_i32 s57, s57, s33
	v_lshl_add_u64 v[162:163], s[16:17], 0, v[0:1]
	s_mov_b32 m0, s57
	ds_read_b128 v[186:189], v196 offset:16384
	ds_read_b128 v[198:201], v196 offset:17408
	ds_read_b128 v[202:205], v196 offset:18432
	ds_read_b128 v[206:209], v196 offset:19456
	ds_read_b128 v[224:227], v196 offset:20480
	ds_read_b128 v[228:231], v196 offset:21504
	ds_read_b128 v[232:235], v196 offset:22528
	ds_read_b128 v[236:239], v196 offset:23552
	global_load_lds_dwordx4 v[162:163], off
	s_add_i32 m0, s57, 0x2000
	s_add_u32 s58, s16, 0x80000
	v_lshl_add_u64 v[164:165], s[16:17], 0, v[146:147]
	s_addc_u32 s59, s17, 0
	s_add_i32 s57, s60, s33
	global_load_lds_dwordx4 v[164:165], off
	s_mov_b32 m0, s57
	v_lshl_add_u64 v[168:169], s[20:21], 0, v[148:149]
	global_load_lds_dwordx4 v0, s[58:59]
	s_add_i32 m0, s57, 0x2000
	s_nop 0
	global_load_lds_dwordx4 v146, s[58:59]
	v_lshl_add_u64 v[166:167], s[20:21], 0, v[150:151]
	s_mov_b32 m0, s26
	s_nop 0
	global_load_lds_dwordx4 v[166:167], off
	s_mov_b32 m0, s27
	s_nop 0
	global_load_lds_dwordx4 v[168:169], off
	s_waitcnt vmcnt(8)
	s_waitcnt lgkmcnt(0)
	s_barrier
	s_setprio 1
	s_waitcnt lgkmcnt(0)
	v_mfma_f32_16x16x32_bf16 v[50:53], v[178:181], v[186:189], v[50:53]
	v_mfma_f32_16x16x32_bf16 v[50:53], v[182:185], v[198:201], v[50:53]
	v_mfma_f32_16x16x32_bf16 v[34:37], v[178:181], v[202:205], v[34:37]
	v_mfma_f32_16x16x32_bf16 v[34:37], v[182:185], v[206:209], v[34:37]
	v_mfma_f32_16x16x32_bf16 v[18:21], v[178:181], v[224:227], v[18:21]
	v_mfma_f32_16x16x32_bf16 v[18:21], v[182:185], v[228:231], v[18:21]
	v_mfma_f32_16x16x32_bf16 v[2:5], v[178:181], v[232:235], v[2:5]
	v_mfma_f32_16x16x32_bf16 v[2:5], v[182:185], v[236:239], v[2:5]
	v_mfma_f32_16x16x32_bf16 v[6:9], v[158:161], v[232:235], v[6:9]
	v_mfma_f32_16x16x32_bf16 v[6:9], v[174:177], v[236:239], v[6:9]
	v_mfma_f32_16x16x32_bf16 v[22:25], v[158:161], v[224:227], v[22:25]
	v_mfma_f32_16x16x32_bf16 v[22:25], v[174:177], v[228:231], v[22:25]
	v_mfma_f32_16x16x32_bf16 v[38:41], v[158:161], v[202:205], v[38:41]
	v_mfma_f32_16x16x32_bf16 v[38:41], v[174:177], v[206:209], v[38:41]
	v_mfma_f32_16x16x32_bf16 v[54:57], v[158:161], v[186:189], v[54:57]
	v_mfma_f32_16x16x32_bf16 v[54:57], v[174:177], v[198:201], v[54:57]
	v_mfma_f32_16x16x32_bf16 v[58:61], v[138:141], v[186:189], v[58:61]
	v_mfma_f32_16x16x32_bf16 v[58:61], v[142:145], v[198:201], v[58:61]
	v_mfma_f32_16x16x32_bf16 v[42:45], v[138:141], v[202:205], v[42:45]
	v_mfma_f32_16x16x32_bf16 v[42:45], v[142:145], v[206:209], v[42:45]
	v_mfma_f32_16x16x32_bf16 v[26:29], v[138:141], v[224:227], v[26:29]
	v_mfma_f32_16x16x32_bf16 v[26:29], v[142:145], v[228:231], v[26:29]
	v_mfma_f32_16x16x32_bf16 v[10:13], v[138:141], v[232:235], v[10:13]
	v_mfma_f32_16x16x32_bf16 v[10:13], v[142:145], v[236:239], v[10:13]
	v_mfma_f32_16x16x32_bf16 v[14:17], v[130:133], v[232:235], v[14:17]
	v_mfma_f32_16x16x32_bf16 v[14:17], v[134:137], v[236:239], v[14:17]
	v_mfma_f32_16x16x32_bf16 v[30:33], v[130:133], v[224:227], v[30:33]
	v_mfma_f32_16x16x32_bf16 v[30:33], v[134:137], v[228:231], v[30:33]
	v_mfma_f32_16x16x32_bf16 v[46:49], v[130:133], v[202:205], v[46:49]
	v_mfma_f32_16x16x32_bf16 v[46:49], v[134:137], v[206:209], v[46:49]
	v_mfma_f32_16x16x32_bf16 v[62:65], v[130:133], v[186:189], v[62:65]
	v_mfma_f32_16x16x32_bf16 v[62:65], v[134:137], v[198:201], v[62:65]
	s_setprio 0
	s_barrier
	s_add_i32 s57, 0, 0x18000
	s_add_i32 s58, 0, 0x1c000
	v_add_u32_e32 v142, s57, v193
	v_add_u32_e32 v170, s58, v193
	ds_read_b128 v[130:133], v142
	ds_read_b128 v[134:137], v142 offset:1024
	ds_read_b128 v[138:141], v142 offset:2048
	ds_read_b128 v[142:145], v142 offset:3072
	ds_read_b128 v[158:161], v170
	ds_read_b128 v[174:177], v170 offset:1024
	ds_read_b128 v[178:181], v170 offset:2048
	ds_read_b128 v[182:185], v170 offset:3072
	s_add_u32 s20, s20, 0x80000
	s_addc_u32 s21, s21, 0
	s_mov_b32 m0, s28
	ds_read_b128 v[186:189], v196 offset:32768
	ds_read_b128 v[198:201], v196 offset:33792
	ds_read_b128 v[202:205], v196 offset:34816
	ds_read_b128 v[206:209], v196 offset:35840
	ds_read_b128 v[224:227], v196 offset:36864
	ds_read_b128 v[228:231], v196 offset:37888
	ds_read_b128 v[232:235], v196 offset:38912
	ds_read_b128 v[236:239], v196 offset:39936
	global_load_lds_dwordx4 v150, s[20:21]
	s_mov_b32 m0, s29
	s_nop 0
	global_load_lds_dwordx4 v148, s[20:21]
	s_waitcnt vmcnt(8)
	s_waitcnt lgkmcnt(0)
	s_barrier
	s_setprio 1
	s_waitcnt lgkmcnt(0)
	v_mfma_f32_16x16x32_bf16 v[126:129], v[130:133], v[186:189], v[126:129]
	v_mfma_f32_16x16x32_bf16 v[126:129], v[134:137], v[198:201], v[126:129]
	v_mfma_f32_16x16x32_bf16 v[110:113], v[130:133], v[202:205], v[110:113]
	v_mfma_f32_16x16x32_bf16 v[110:113], v[134:137], v[206:209], v[110:113]
	v_mfma_f32_16x16x32_bf16 v[94:97], v[130:133], v[224:227], v[94:97]
	v_mfma_f32_16x16x32_bf16 v[94:97], v[134:137], v[228:231], v[94:97]
	v_mfma_f32_16x16x32_bf16 v[78:81], v[130:133], v[232:235], v[78:81]
	v_mfma_f32_16x16x32_bf16 v[78:81], v[134:137], v[236:239], v[78:81]
	v_mfma_f32_16x16x32_bf16 v[74:77], v[138:141], v[232:235], v[74:77]
	v_mfma_f32_16x16x32_bf16 v[74:77], v[142:145], v[236:239], v[74:77]
	v_mfma_f32_16x16x32_bf16 v[90:93], v[138:141], v[224:227], v[90:93]
	v_mfma_f32_16x16x32_bf16 v[90:93], v[142:145], v[228:231], v[90:93]
	v_mfma_f32_16x16x32_bf16 v[106:109], v[138:141], v[202:205], v[106:109]
	v_mfma_f32_16x16x32_bf16 v[106:109], v[142:145], v[206:209], v[106:109]
	v_mfma_f32_16x16x32_bf16 v[122:125], v[138:141], v[186:189], v[122:125]
	v_mfma_f32_16x16x32_bf16 v[122:125], v[142:145], v[198:201], v[122:125]
	v_mfma_f32_16x16x32_bf16 v[118:121], v[158:161], v[186:189], v[118:121]
	v_mfma_f32_16x16x32_bf16 v[118:121], v[174:177], v[198:201], v[118:121]
	v_mfma_f32_16x16x32_bf16 v[102:105], v[158:161], v[202:205], v[102:105]
	v_mfma_f32_16x16x32_bf16 v[102:105], v[174:177], v[206:209], v[102:105]
	v_mfma_f32_16x16x32_bf16 v[86:89], v[158:161], v[224:227], v[86:89]
	v_mfma_f32_16x16x32_bf16 v[86:89], v[174:177], v[228:231], v[86:89]
	v_mfma_f32_16x16x32_bf16 v[70:73], v[158:161], v[232:235], v[70:73]
	v_mfma_f32_16x16x32_bf16 v[70:73], v[174:177], v[236:239], v[70:73]
	v_mfma_f32_16x16x32_bf16 v[66:69], v[178:181], v[232:235], v[66:69]
	v_mfma_f32_16x16x32_bf16 v[66:69], v[182:185], v[236:239], v[66:69]
	v_mfma_f32_16x16x32_bf16 v[82:85], v[178:181], v[224:227], v[82:85]
	v_mfma_f32_16x16x32_bf16 v[82:85], v[182:185], v[228:231], v[82:85]
	v_mfma_f32_16x16x32_bf16 v[98:101], v[178:181], v[202:205], v[98:101]
	v_mfma_f32_16x16x32_bf16 v[98:101], v[182:185], v[206:209], v[98:101]
	v_mfma_f32_16x16x32_bf16 v[114:117], v[178:181], v[186:189], v[114:117]
	v_mfma_f32_16x16x32_bf16 v[114:117], v[182:185], v[198:201], v[114:117]
	s_setprio 0
	s_barrier
	s_add_i32 s20, s57, s33
	v_lshl_add_u64 v[162:163], v[162:163], 0, s[30:31]
	s_mov_b32 m0, s20
	ds_read_b128 v[186:189], v196 offset:49152
	ds_read_b128 v[198:201], v196 offset:50176
	ds_read_b128 v[202:205], v196 offset:51200
	ds_read_b128 v[206:209], v196 offset:52224
	ds_read_b128 v[224:227], v196 offset:53248
	ds_read_b128 v[228:231], v196 offset:54272
	ds_read_b128 v[232:235], v196 offset:55296
	ds_read_b128 v[236:239], v196 offset:56320
	global_load_lds_dwordx4 v[162:163], off
	s_add_i32 m0, s20, 0x2000
	s_add_u32 s16, s16, 0x80080
	v_lshl_add_u64 v[162:163], v[164:165], 0, s[30:31]
	s_addc_u32 s17, s17, 0
	s_add_i32 s20, s58, s33
	global_load_lds_dwordx4 v[162:163], off
	s_mov_b32 m0, s20
	s_nop 0
	global_load_lds_dwordx4 v0, s[16:17]
	s_add_i32 m0, s20, 0x2000
	s_nop 0
	global_load_lds_dwordx4 v146, s[16:17]
	v_lshl_add_u64 v[162:163], v[166:167], 0, s[30:31]
	s_mov_b32 m0, s48
	s_nop 0
	global_load_lds_dwordx4 v[162:163], off
	v_lshl_add_u64 v[162:163], v[168:169], 0, s[30:31]
	s_mov_b32 m0, s49
	s_nop 0
	global_load_lds_dwordx4 v[162:163], off
	s_waitcnt vmcnt(8)
	s_waitcnt lgkmcnt(0)
	s_barrier
	s_setprio 1
	s_waitcnt lgkmcnt(0)
	v_mfma_f32_16x16x32_bf16 v[50:53], v[178:181], v[186:189], v[50:53]
	v_mfma_f32_16x16x32_bf16 v[50:53], v[182:185], v[198:201], v[50:53]
	v_mfma_f32_16x16x32_bf16 v[34:37], v[178:181], v[202:205], v[34:37]
	v_mfma_f32_16x16x32_bf16 v[34:37], v[182:185], v[206:209], v[34:37]
	v_mfma_f32_16x16x32_bf16 v[18:21], v[178:181], v[224:227], v[18:21]
	v_mfma_f32_16x16x32_bf16 v[18:21], v[182:185], v[228:231], v[18:21]
	v_mfma_f32_16x16x32_bf16 v[2:5], v[178:181], v[232:235], v[2:5]
	v_mfma_f32_16x16x32_bf16 v[2:5], v[182:185], v[236:239], v[2:5]
	v_mfma_f32_16x16x32_bf16 v[6:9], v[158:161], v[232:235], v[6:9]
	v_mfma_f32_16x16x32_bf16 v[6:9], v[174:177], v[236:239], v[6:9]
	v_mfma_f32_16x16x32_bf16 v[22:25], v[158:161], v[224:227], v[22:25]
	v_mfma_f32_16x16x32_bf16 v[22:25], v[174:177], v[228:231], v[22:25]
	v_mfma_f32_16x16x32_bf16 v[38:41], v[158:161], v[202:205], v[38:41]
	v_mfma_f32_16x16x32_bf16 v[38:41], v[174:177], v[206:209], v[38:41]
	v_mfma_f32_16x16x32_bf16 v[54:57], v[158:161], v[186:189], v[54:57]
	v_mfma_f32_16x16x32_bf16 v[54:57], v[174:177], v[198:201], v[54:57]
	v_mfma_f32_16x16x32_bf16 v[58:61], v[138:141], v[186:189], v[58:61]
	v_mfma_f32_16x16x32_bf16 v[58:61], v[142:145], v[198:201], v[58:61]
	v_mfma_f32_16x16x32_bf16 v[42:45], v[138:141], v[202:205], v[42:45]
	v_mfma_f32_16x16x32_bf16 v[42:45], v[142:145], v[206:209], v[42:45]
	v_mfma_f32_16x16x32_bf16 v[26:29], v[138:141], v[224:227], v[26:29]
	v_mfma_f32_16x16x32_bf16 v[26:29], v[142:145], v[228:231], v[26:29]
	v_mfma_f32_16x16x32_bf16 v[10:13], v[138:141], v[232:235], v[10:13]
	v_mfma_f32_16x16x32_bf16 v[10:13], v[142:145], v[236:239], v[10:13]
	v_mfma_f32_16x16x32_bf16 v[14:17], v[130:133], v[232:235], v[14:17]
	v_mfma_f32_16x16x32_bf16 v[14:17], v[134:137], v[236:239], v[14:17]
	v_mfma_f32_16x16x32_bf16 v[30:33], v[130:133], v[224:227], v[30:33]
	v_mfma_f32_16x16x32_bf16 v[30:33], v[134:137], v[228:231], v[30:33]
	v_mfma_f32_16x16x32_bf16 v[46:49], v[130:133], v[202:205], v[46:49]
	v_mfma_f32_16x16x32_bf16 v[46:49], v[134:137], v[206:209], v[46:49]
	v_mfma_f32_16x16x32_bf16 v[62:65], v[130:133], v[186:189], v[62:65]
	v_mfma_f32_16x16x32_bf16 v[62:65], v[134:137], v[198:201], v[62:65]
	s_setprio 0
	s_barrier
	s_add_i32 s56, s56, 2
	s_add_u32 s6, s6, 0x100
	s_addc_u32 s7, s7, 0
	s_add_u32 s54, s54, 0x100
	s_addc_u32 s55, s55, 0
	s_cmp_gt_u32 s56, 29
	s_cbranch_scc0 .LBB0_665
	v_readlane_b32 s6, v253, 2
	v_readlane_b32 s7, v253, 3
	s_and_b64 vcc, exec, s[6:7]
	s_cbranch_vccz .LBB0_670
	s_barrier
	s_cmp_lt_i32 s51, 22
	s_mov_b64 s[6:7], -1
	s_cbranch_scc1 .LBB0_671

.LBB0_1913:
	s_add_i32 s52, s20, 2
	s_add_u32 s14, s16, 0xfff80080
	s_addc_u32 s15, s17, -1
	s_add_i32 s53, 0, 0x10000
	s_cmp_eq_u32 s49, s20
	s_cselect_b32 s21, s7, s15
	s_cselect_b32 s20, s6, s14
	v_add_u32_e32 v0, s53, v189
	s_cselect_b32 s15, s13, s51
	s_cselect_b32 s14, s12, s50
	s_add_i32 s56, 0, 0x14000
	ds_read_b128 v[132:135], v0
	ds_read_b128 v[148:151], v0 offset:1024
	ds_read_b128 v[152:155], v0 offset:2048
	ds_read_b128 v[156:159], v0 offset:3072
	v_add_u32_e32 v0, s56, v189
	ds_read_b128 v[160:163], v0
	ds_read_b128 v[164:167], v0 offset:1024
	ds_read_b128 v[168:171], v0 offset:2048
	ds_read_b128 v[172:175], v0 offset:3072
	s_add_i32 m0, s26, 0xc000
	ds_read_b128 v[176:179], v191
	ds_read_b128 v[180:183], v191 offset:1024
	ds_read_b128 v[184:187], v191 offset:2048
	ds_read_b128 v[192:195], v191 offset:3072
	ds_read_b128 v[196:199], v191 offset:4096
	ds_read_b128 v[200:203], v191 offset:5120
	ds_read_b128 v[204:207], v191 offset:6144
	ds_read_b128 v[208:211], v191 offset:7168
	global_load_lds_dwordx4 v144, s[16:17]
	s_add_i32 m0, s26, 0xe000
	s_nop 0
	global_load_lds_dwordx4 v146, s[16:17]
	s_waitcnt vmcnt(8)
	s_waitcnt lgkmcnt(0)
	s_barrier
	s_setprio 1
	s_waitcnt lgkmcnt(0)
	v_mfma_f32_16x16x32_bf16 v[128:131], v[132:135], v[176:179], v[128:131]
	v_mfma_f32_16x16x32_bf16 v[128:131], v[148:151], v[180:183], v[128:131]
	v_mfma_f32_16x16x32_bf16 v[120:123], v[132:135], v[184:187], v[120:123]
	v_mfma_f32_16x16x32_bf16 v[120:123], v[148:151], v[192:195], v[120:123]
	v_mfma_f32_16x16x32_bf16 v[112:115], v[132:135], v[196:199], v[112:115]
	v_mfma_f32_16x16x32_bf16 v[112:115], v[148:151], v[200:203], v[112:115]
	v_mfma_f32_16x16x32_bf16 v[104:107], v[132:135], v[204:207], v[104:107]
	v_mfma_f32_16x16x32_bf16 v[104:107], v[148:151], v[208:211], v[104:107]
	v_mfma_f32_16x16x32_bf16 v[100:103], v[152:155], v[204:207], v[100:103]
	v_mfma_f32_16x16x32_bf16 v[100:103], v[156:159], v[208:211], v[100:103]
	v_mfma_f32_16x16x32_bf16 v[108:111], v[152:155], v[196:199], v[108:111]
	v_mfma_f32_16x16x32_bf16 v[108:111], v[156:159], v[200:203], v[108:111]
	v_mfma_f32_16x16x32_bf16 v[116:119], v[152:155], v[184:187], v[116:119]
	v_mfma_f32_16x16x32_bf16 v[116:119], v[156:159], v[192:195], v[116:119]
	v_mfma_f32_16x16x32_bf16 v[124:127], v[152:155], v[176:179], v[124:127]
	v_mfma_f32_16x16x32_bf16 v[124:127], v[156:159], v[180:183], v[124:127]
	v_mfma_f32_16x16x32_bf16 v[96:99], v[160:163], v[176:179], v[96:99]
	v_mfma_f32_16x16x32_bf16 v[96:99], v[164:167], v[180:183], v[96:99]
	v_mfma_f32_16x16x32_bf16 v[88:91], v[160:163], v[184:187], v[88:91]
	v_mfma_f32_16x16x32_bf16 v[88:91], v[164:167], v[192:195], v[88:91]
	v_mfma_f32_16x16x32_bf16 v[80:83], v[160:163], v[196:199], v[80:83]
	v_mfma_f32_16x16x32_bf16 v[80:83], v[164:167], v[200:203], v[80:83]
	v_mfma_f32_16x16x32_bf16 v[72:75], v[160:163], v[204:207], v[72:75]
	v_mfma_f32_16x16x32_bf16 v[72:75], v[164:167], v[208:211], v[72:75]
	v_mfma_f32_16x16x32_bf16 v[68:71], v[168:171], v[204:207], v[68:71]
	v_mfma_f32_16x16x32_bf16 v[68:71], v[172:175], v[208:211], v[68:71]
	v_mfma_f32_16x16x32_bf16 v[76:79], v[168:171], v[196:199], v[76:79]
	v_mfma_f32_16x16x32_bf16 v[76:79], v[172:175], v[200:203], v[76:79]
	v_mfma_f32_16x16x32_bf16 v[84:87], v[168:171], v[184:187], v[84:87]
	v_mfma_f32_16x16x32_bf16 v[84:87], v[172:175], v[192:195], v[84:87]
	v_mfma_f32_16x16x32_bf16 v[92:95], v[168:171], v[176:179], v[92:95]
	v_mfma_f32_16x16x32_bf16 v[92:95], v[172:175], v[180:183], v[92:95]
	s_setprio 0
	s_barrier
	s_add_i32 s53, s53, s33
	v_lshl_add_u64 v[212:213], s[14:15], 0, v[140:141]
	s_mov_b32 m0, s53
	ds_read_b128 v[176:179], v191 offset:16384
	ds_read_b128 v[180:183], v191 offset:17408
	ds_read_b128 v[184:187], v191 offset:18432
	ds_read_b128 v[192:195], v191 offset:19456
	ds_read_b128 v[196:199], v191 offset:20480
	ds_read_b128 v[200:203], v191 offset:21504
	ds_read_b128 v[204:207], v191 offset:22528
	ds_read_b128 v[208:211], v191 offset:23552
	global_load_lds_dwordx4 v[212:213], off
	s_add_i32 m0, s53, 0x2000
	s_add_u32 s54, s14, 0x80000
	v_lshl_add_u64 v[220:221], s[14:15], 0, v[136:137]
	s_addc_u32 s55, s15, 0
	s_add_i32 s53, s56, s33
	global_load_lds_dwordx4 v[220:221], off
	s_mov_b32 m0, s53
	v_lshl_add_u64 v[224:225], s[20:21], 0, v[142:143]
	global_load_lds_dwordx4 v140, s[54:55]
	s_add_i32 m0, s53, 0x2000
	v_lshl_add_u64 v[226:227], s[20:21], 0, v[138:139]
	global_load_lds_dwordx4 v136, s[54:55]
	s_mov_b32 m0, s26
	s_nop 0
	global_load_lds_dwordx4 v[224:225], off
	s_mov_b32 m0, s27
	s_nop 0
	global_load_lds_dwordx4 v[226:227], off
	s_waitcnt vmcnt(8)
	s_waitcnt lgkmcnt(0)
	s_barrier
	s_setprio 1
	s_waitcnt lgkmcnt(0)
	v_mfma_f32_16x16x32_bf16 v[28:31], v[168:171], v[176:179], v[28:31]
	v_mfma_f32_16x16x32_bf16 v[28:31], v[172:175], v[180:183], v[28:31]
	v_mfma_f32_16x16x32_bf16 v[20:23], v[168:171], v[184:187], v[20:23]
	v_mfma_f32_16x16x32_bf16 v[20:23], v[172:175], v[192:195], v[20:23]
	v_mfma_f32_16x16x32_bf16 v[12:15], v[168:171], v[196:199], v[12:15]
	v_mfma_f32_16x16x32_bf16 v[12:15], v[172:175], v[200:203], v[12:15]
	v_mfma_f32_16x16x32_bf16 v[2:5], v[168:171], v[204:207], v[4:7]
	v_mfma_f32_16x16x32_bf16 v[2:5], v[172:175], v[208:211], v[2:5]
	v_mfma_f32_16x16x32_bf16 v[8:11], v[160:163], v[204:207], v[8:11]
	v_mfma_f32_16x16x32_bf16 v[8:11], v[164:167], v[208:211], v[8:11]
	v_mfma_f32_16x16x32_bf16 v[16:19], v[160:163], v[196:199], v[16:19]
	v_mfma_f32_16x16x32_bf16 v[16:19], v[164:167], v[200:203], v[16:19]
	v_mfma_f32_16x16x32_bf16 v[24:27], v[160:163], v[184:187], v[24:27]
	v_mfma_f32_16x16x32_bf16 v[24:27], v[164:167], v[192:195], v[24:27]
	v_mfma_f32_16x16x32_bf16 v[32:35], v[160:163], v[176:179], v[32:35]
	v_mfma_f32_16x16x32_bf16 v[32:35], v[164:167], v[180:183], v[32:35]
	v_mfma_f32_16x16x32_bf16 v[60:63], v[152:155], v[176:179], v[60:63]
	v_mfma_f32_16x16x32_bf16 v[60:63], v[156:159], v[180:183], v[60:63]
	v_mfma_f32_16x16x32_bf16 v[52:55], v[152:155], v[184:187], v[52:55]
	v_mfma_f32_16x16x32_bf16 v[52:55], v[156:159], v[192:195], v[52:55]
	v_mfma_f32_16x16x32_bf16 v[44:47], v[152:155], v[196:199], v[44:47]
	v_mfma_f32_16x16x32_bf16 v[44:47], v[156:159], v[200:203], v[44:47]
	v_mfma_f32_16x16x32_bf16 v[36:39], v[152:155], v[204:207], v[36:39]
	v_mfma_f32_16x16x32_bf16 v[36:39], v[156:159], v[208:211], v[36:39]
	v_mfma_f32_16x16x32_bf16 v[40:43], v[132:135], v[204:207], v[40:43]
	v_mfma_f32_16x16x32_bf16 v[40:43], v[148:151], v[208:211], v[40:43]
	v_mfma_f32_16x16x32_bf16 v[48:51], v[132:135], v[196:199], v[48:51]
	v_mfma_f32_16x16x32_bf16 v[48:51], v[148:151], v[200:203], v[48:51]
	v_mfma_f32_16x16x32_bf16 v[56:59], v[132:135], v[184:187], v[56:59]
	v_mfma_f32_16x16x32_bf16 v[56:59], v[148:151], v[192:195], v[56:59]
	v_mfma_f32_16x16x32_bf16 v[64:67], v[132:135], v[176:179], v[64:67]
	v_mfma_f32_16x16x32_bf16 v[64:67], v[148:151], v[180:183], v[64:67]
	s_setprio 0
	s_barrier
	s_add_i32 s53, 0, 0x18000
	v_add_u32_e32 v0, s53, v189
	s_add_i32 s54, 0, 0x1c000
	ds_read_b128 v[132:135], v0
	ds_read_b128 v[148:151], v0 offset:1024
	ds_read_b128 v[152:155], v0 offset:2048
	ds_read_b128 v[156:159], v0 offset:3072
	v_add_u32_e32 v0, s54, v189
	ds_read_b128 v[160:163], v0
	ds_read_b128 v[164:167], v0 offset:1024
	ds_read_b128 v[168:171], v0 offset:2048
	ds_read_b128 v[172:175], v0 offset:3072
	s_add_u32 s20, s20, 0x80000
	s_addc_u32 s21, s21, 0
	s_mov_b32 m0, s28
	ds_read_b128 v[176:179], v191 offset:32768
	ds_read_b128 v[180:183], v191 offset:33792
	ds_read_b128 v[184:187], v191 offset:34816
	ds_read_b128 v[192:195], v191 offset:35840
	ds_read_b128 v[196:199], v191 offset:36864
	ds_read_b128 v[200:203], v191 offset:37888
	ds_read_b128 v[204:207], v191 offset:38912
	ds_read_b128 v[208:211], v191 offset:39936
	global_load_lds_dwordx4 v142, s[20:21]
	s_mov_b32 m0, s29
	s_nop 0
	global_load_lds_dwordx4 v138, s[20:21]
	s_waitcnt vmcnt(8)
	s_waitcnt lgkmcnt(0)
	s_barrier
	s_setprio 1
	s_waitcnt lgkmcnt(0)
	v_mfma_f32_16x16x32_bf16 v[128:131], v[132:135], v[176:179], v[128:131]
	v_mfma_f32_16x16x32_bf16 v[128:131], v[148:151], v[180:183], v[128:131]
	v_mfma_f32_16x16x32_bf16 v[120:123], v[132:135], v[184:187], v[120:123]
	v_mfma_f32_16x16x32_bf16 v[120:123], v[148:151], v[192:195], v[120:123]
	v_mfma_f32_16x16x32_bf16 v[112:115], v[132:135], v[196:199], v[112:115]
	v_mfma_f32_16x16x32_bf16 v[112:115], v[148:151], v[200:203], v[112:115]
	v_mfma_f32_16x16x32_bf16 v[104:107], v[132:135], v[204:207], v[104:107]
	v_mfma_f32_16x16x32_bf16 v[104:107], v[148:151], v[208:211], v[104:107]
	v_mfma_f32_16x16x32_bf16 v[100:103], v[152:155], v[204:207], v[100:103]
	v_mfma_f32_16x16x32_bf16 v[100:103], v[156:159], v[208:211], v[100:103]
	v_mfma_f32_16x16x32_bf16 v[108:111], v[152:155], v[196:199], v[108:111]
	v_mfma_f32_16x16x32_bf16 v[108:111], v[156:159], v[200:203], v[108:111]
	v_mfma_f32_16x16x32_bf16 v[116:119], v[152:155], v[184:187], v[116:119]
	v_mfma_f32_16x16x32_bf16 v[116:119], v[156:159], v[192:195], v[116:119]
	v_mfma_f32_16x16x32_bf16 v[124:127], v[152:155], v[176:179], v[124:127]
	v_mfma_f32_16x16x32_bf16 v[124:127], v[156:159], v[180:183], v[124:127]
	v_mfma_f32_16x16x32_bf16 v[96:99], v[160:163], v[176:179], v[96:99]
	v_mfma_f32_16x16x32_bf16 v[96:99], v[164:167], v[180:183], v[96:99]
	v_mfma_f32_16x16x32_bf16 v[88:91], v[160:163], v[184:187], v[88:91]
	v_mfma_f32_16x16x32_bf16 v[88:91], v[164:167], v[192:195], v[88:91]
	v_mfma_f32_16x16x32_bf16 v[80:83], v[160:163], v[196:199], v[80:83]
	v_mfma_f32_16x16x32_bf16 v[80:83], v[164:167], v[200:203], v[80:83]
	v_mfma_f32_16x16x32_bf16 v[72:75], v[160:163], v[204:207], v[72:75]
	v_mfma_f32_16x16x32_bf16 v[72:75], v[164:167], v[208:211], v[72:75]
	v_mfma_f32_16x16x32_bf16 v[68:71], v[168:171], v[204:207], v[68:71]
	v_mfma_f32_16x16x32_bf16 v[68:71], v[172:175], v[208:211], v[68:71]
	v_mfma_f32_16x16x32_bf16 v[76:79], v[168:171], v[196:199], v[76:79]
	v_mfma_f32_16x16x32_bf16 v[76:79], v[172:175], v[200:203], v[76:79]
	v_mfma_f32_16x16x32_bf16 v[84:87], v[168:171], v[184:187], v[84:87]
	v_mfma_f32_16x16x32_bf16 v[84:87], v[172:175], v[192:195], v[84:87]
	v_mfma_f32_16x16x32_bf16 v[92:95], v[168:171], v[176:179], v[92:95]
	v_mfma_f32_16x16x32_bf16 v[92:95], v[172:175], v[180:183], v[92:95]
	s_setprio 0
	s_barrier
	s_add_i32 s20, s53, s33
	v_lshl_add_u64 v[6:7], v[212:213], 0, s[30:31]
	s_mov_b32 m0, s20
	ds_read_b128 v[176:179], v191 offset:49152
	ds_read_b128 v[180:183], v191 offset:50176
	ds_read_b128 v[184:187], v191 offset:51200
	ds_read_b128 v[192:195], v191 offset:52224
	ds_read_b128 v[196:199], v191 offset:53248
	ds_read_b128 v[200:203], v191 offset:54272
	ds_read_b128 v[204:207], v191 offset:55296
	ds_read_b128 v[208:211], v191 offset:56320
	global_load_lds_dwordx4 v[6:7], off
	s_add_i32 m0, s20, 0x2000
	s_add_u32 s14, s14, 0x80080
	v_lshl_add_u64 v[6:7], v[220:221], 0, s[30:31]
	s_addc_u32 s15, s15, 0
	s_add_i32 s20, s54, s33
	global_load_lds_dwordx4 v[6:7], off
	s_mov_b32 m0, s20
	s_nop 0
	global_load_lds_dwordx4 v140, s[14:15]
	s_add_i32 m0, s20, 0x2000
	s_nop 0
	global_load_lds_dwordx4 v136, s[14:15]
	v_lshl_add_u64 v[6:7], v[224:225], 0, s[30:31]
	s_mov_b32 m0, s34
	s_nop 0
	global_load_lds_dwordx4 v[6:7], off
	v_lshl_add_u64 v[6:7], v[226:227], 0, s[30:31]
	s_mov_b32 m0, s35
	s_nop 0
	global_load_lds_dwordx4 v[6:7], off
	s_waitcnt vmcnt(8)
	s_waitcnt lgkmcnt(0)
	s_barrier
	s_setprio 1
	s_waitcnt lgkmcnt(0)
	v_mfma_f32_16x16x32_bf16 v[28:31], v[168:171], v[176:179], v[28:31]
	v_mfma_f32_16x16x32_bf16 v[28:31], v[172:175], v[180:183], v[28:31]
	v_mfma_f32_16x16x32_bf16 v[20:23], v[168:171], v[184:187], v[20:23]
	v_mfma_f32_16x16x32_bf16 v[20:23], v[172:175], v[192:195], v[20:23]
	v_mfma_f32_16x16x32_bf16 v[12:15], v[168:171], v[196:199], v[12:15]
	v_mfma_f32_16x16x32_bf16 v[12:15], v[172:175], v[200:203], v[12:15]
	v_mfma_f32_16x16x32_bf16 v[6:9], v[160:163], v[204:207], v[8:11]
	v_mfma_f32_16x16x32_bf16 v[8:11], v[164:167], v[208:211], v[6:9]
	v_mfma_f32_16x16x32_bf16 v[2:5], v[168:171], v[204:207], v[2:5]
	v_mfma_f32_16x16x32_bf16 v[4:7], v[172:175], v[208:211], v[2:5]
	v_mfma_f32_16x16x32_bf16 v[16:19], v[160:163], v[196:199], v[16:19]
	v_mfma_f32_16x16x32_bf16 v[16:19], v[164:167], v[200:203], v[16:19]
	v_mfma_f32_16x16x32_bf16 v[24:27], v[160:163], v[184:187], v[24:27]
	v_mfma_f32_16x16x32_bf16 v[24:27], v[164:167], v[192:195], v[24:27]
	v_mfma_f32_16x16x32_bf16 v[32:35], v[160:163], v[176:179], v[32:35]
	v_mfma_f32_16x16x32_bf16 v[32:35], v[164:167], v[180:183], v[32:35]
	v_mfma_f32_16x16x32_bf16 v[60:63], v[152:155], v[176:179], v[60:63]
	v_mfma_f32_16x16x32_bf16 v[60:63], v[156:159], v[180:183], v[60:63]
	v_mfma_f32_16x16x32_bf16 v[52:55], v[152:155], v[184:187], v[52:55]
	v_mfma_f32_16x16x32_bf16 v[52:55], v[156:159], v[192:195], v[52:55]
	v_mfma_f32_16x16x32_bf16 v[44:47], v[152:155], v[196:199], v[44:47]
	v_mfma_f32_16x16x32_bf16 v[44:47], v[156:159], v[200:203], v[44:47]
	v_mfma_f32_16x16x32_bf16 v[36:39], v[152:155], v[204:207], v[36:39]
	v_mfma_f32_16x16x32_bf16 v[36:39], v[156:159], v[208:211], v[36:39]
	v_mfma_f32_16x16x32_bf16 v[40:43], v[132:135], v[204:207], v[40:43]
	v_mfma_f32_16x16x32_bf16 v[40:43], v[148:151], v[208:211], v[40:43]
	v_mfma_f32_16x16x32_bf16 v[48:51], v[132:135], v[196:199], v[48:51]
	v_mfma_f32_16x16x32_bf16 v[48:51], v[148:151], v[200:203], v[48:51]
	v_mfma_f32_16x16x32_bf16 v[56:59], v[132:135], v[184:187], v[56:59]
	v_mfma_f32_16x16x32_bf16 v[56:59], v[148:151], v[192:195], v[56:59]
	v_mfma_f32_16x16x32_bf16 v[64:67], v[132:135], v[176:179], v[64:67]
	v_mfma_f32_16x16x32_bf16 v[64:67], v[148:151], v[180:183], v[64:67]
	s_setprio 0
	s_barrier
	s_add_u32 s16, s16, 0x100
	s_addc_u32 s17, s17, 0
	s_add_u32 s50, s50, 0x100
	s_addc_u32 s51, s51, 0
	s_cmp_ge_u32 s52, s11
	s_mov_b32 s20, s52
	s_cbranch_scc0 .LBB0_1913
	v_readlane_b32 s14, v253, 2
	v_readlane_b32 s15, v253, 3
	s_and_b64 vcc, exec, s[14:15]
	s_cbranch_vccz .LBB0_1916
	s_barrier

.LBB0_1997:
	s_add_u32 s22, s16, 0xfff80080
	s_addc_u32 s23, s17, -1
	s_add_i32 s69, 0, 0x10000
	s_cmp_eq_u32 s25, 28
	s_cselect_b32 s27, s11, s23
	s_cselect_b32 s26, s18, s22
	s_cselect_b32 s23, s9, s24
	s_cselect_b32 s22, s19, s21
	s_add_i32 s72, 0, 0x14000
	v_add_u32_e32 v142, s69, v205
	v_add_u32_e32 v162, s72, v205
	ds_read_b128 v[130:133], v142
	ds_read_b128 v[134:137], v142 offset:1024
	ds_read_b128 v[138:141], v142 offset:2048
	ds_read_b128 v[142:145], v142 offset:3072
	ds_read_b128 v[146:149], v162
	ds_read_b128 v[150:153], v162 offset:1024
	ds_read_b128 v[154:157], v162 offset:2048
	ds_read_b128 v[162:165], v162 offset:3072
	s_add_i32 m0, s54, 0xc000
	ds_read_b128 v[166:169], v230
	ds_read_b128 v[170:173], v230 offset:1024
	ds_read_b128 v[184:187], v230 offset:2048
	ds_read_b128 v[188:191], v230 offset:3072
	ds_read_b128 v[192:195], v230 offset:4096
	ds_read_b128 v[196:199], v230 offset:5120
	ds_read_b128 v[200:203], v230 offset:6144
	ds_read_b128 v[232:235], v230 offset:7168
	global_load_lds_dwordx4 v180, s[16:17]
	s_add_i32 m0, s54, 0xe000
	s_nop 0
	global_load_lds_dwordx4 v182, s[16:17]
	s_waitcnt vmcnt(8)
	s_waitcnt lgkmcnt(0)
	s_barrier
	s_setprio 1
	s_waitcnt lgkmcnt(0)
	v_mfma_f32_16x16x32_bf16 v[126:129], v[130:133], v[166:169], v[126:129]
	v_mfma_f32_16x16x32_bf16 v[126:129], v[134:137], v[170:173], v[126:129]
	v_mfma_f32_16x16x32_bf16 v[118:121], v[130:133], v[184:187], v[118:121]
	v_mfma_f32_16x16x32_bf16 v[118:121], v[134:137], v[188:191], v[118:121]
	v_mfma_f32_16x16x32_bf16 v[110:113], v[130:133], v[192:195], v[110:113]
	v_mfma_f32_16x16x32_bf16 v[110:113], v[134:137], v[196:199], v[110:113]
	v_mfma_f32_16x16x32_bf16 v[102:105], v[130:133], v[200:203], v[102:105]
	v_mfma_f32_16x16x32_bf16 v[102:105], v[134:137], v[232:235], v[102:105]
	v_mfma_f32_16x16x32_bf16 v[38:41], v[138:141], v[200:203], v[38:41]
	v_mfma_f32_16x16x32_bf16 v[38:41], v[142:145], v[232:235], v[38:41]
	v_mfma_f32_16x16x32_bf16 v[66:69], v[138:141], v[192:195], v[66:69]
	v_mfma_f32_16x16x32_bf16 v[66:69], v[142:145], v[196:199], v[66:69]
	v_mfma_f32_16x16x32_bf16 v[86:89], v[138:141], v[184:187], v[86:89]
	v_mfma_f32_16x16x32_bf16 v[86:89], v[142:145], v[188:191], v[86:89]
	v_mfma_f32_16x16x32_bf16 v[74:77], v[138:141], v[166:169], v[74:77]
	v_mfma_f32_16x16x32_bf16 v[74:77], v[142:145], v[170:173], v[74:77]
	v_mfma_f32_16x16x32_bf16 v[122:125], v[146:149], v[166:169], v[122:125]
	v_mfma_f32_16x16x32_bf16 v[122:125], v[150:153], v[170:173], v[122:125]
	v_mfma_f32_16x16x32_bf16 v[114:117], v[146:149], v[184:187], v[114:117]
	v_mfma_f32_16x16x32_bf16 v[114:117], v[150:153], v[188:191], v[114:117]
	v_mfma_f32_16x16x32_bf16 v[106:109], v[146:149], v[192:195], v[106:109]
	v_mfma_f32_16x16x32_bf16 v[106:109], v[150:153], v[196:199], v[106:109]
	v_mfma_f32_16x16x32_bf16 v[98:101], v[146:149], v[200:203], v[98:101]
	v_mfma_f32_16x16x32_bf16 v[98:101], v[150:153], v[232:235], v[98:101]
	v_mfma_f32_16x16x32_bf16 v[42:45], v[154:157], v[200:203], v[42:45]
	v_mfma_f32_16x16x32_bf16 v[42:45], v[162:165], v[232:235], v[42:45]
	v_mfma_f32_16x16x32_bf16 v[70:73], v[154:157], v[192:195], v[70:73]
	v_mfma_f32_16x16x32_bf16 v[70:73], v[162:165], v[196:199], v[70:73]
	v_mfma_f32_16x16x32_bf16 v[90:93], v[154:157], v[184:187], v[90:93]
	v_mfma_f32_16x16x32_bf16 v[90:93], v[162:165], v[188:191], v[90:93]
	v_mfma_f32_16x16x32_bf16 v[82:85], v[154:157], v[166:169], v[82:85]
	v_mfma_f32_16x16x32_bf16 v[82:85], v[162:165], v[170:173], v[82:85]
	s_setprio 0
	s_barrier
	s_add_i32 s69, s69, s33
	v_lshl_add_u64 v[212:213], s[22:23], 0, v[0:1]
	s_mov_b32 m0, s69
	ds_read_b128 v[166:169], v230 offset:16384
	ds_read_b128 v[170:173], v230 offset:17408
	ds_read_b128 v[184:187], v230 offset:18432
	ds_read_b128 v[188:191], v230 offset:19456
	ds_read_b128 v[192:195], v230 offset:20480
	ds_read_b128 v[196:199], v230 offset:21504
	ds_read_b128 v[200:203], v230 offset:22528
	ds_read_b128 v[232:235], v230 offset:23552
	global_load_lds_dwordx4 v[212:213], off
	s_add_i32 m0, s69, 0x2000
	s_add_u32 s70, s22, 0x80000
	v_lshl_add_u64 v[220:221], s[22:23], 0, v[158:159]
	s_addc_u32 s71, s23, 0
	s_add_i32 s69, s72, s33
	global_load_lds_dwordx4 v[220:221], off
	s_mov_b32 m0, s69
	v_lshl_add_u64 v[238:239], s[26:27], 0, v[160:161]
	global_load_lds_dwordx4 v0, s[70:71]
	s_add_i32 m0, s69, 0x2000
	s_nop 0
	global_load_lds_dwordx4 v158, s[70:71]
	v_lshl_add_u64 v[236:237], s[26:27], 0, v[174:175]
	s_mov_b32 m0, s54
	s_nop 0
	global_load_lds_dwordx4 v[236:237], off
	s_mov_b32 m0, s55
	s_nop 0
	global_load_lds_dwordx4 v[238:239], off
	s_waitcnt vmcnt(8)
	s_waitcnt lgkmcnt(0)
	s_barrier
	s_setprio 1
	s_waitcnt lgkmcnt(0)
	v_mfma_f32_16x16x32_bf16 v[58:61], v[154:157], v[166:169], v[58:61]
	v_mfma_f32_16x16x32_bf16 v[58:61], v[162:165], v[170:173], v[58:61]
	v_mfma_f32_16x16x32_bf16 v[34:37], v[154:157], v[184:187], v[34:37]
	v_mfma_f32_16x16x32_bf16 v[34:37], v[162:165], v[188:191], v[34:37]
	v_mfma_f32_16x16x32_bf16 v[14:17], v[154:157], v[192:195], v[14:17]
	v_mfma_f32_16x16x32_bf16 v[14:17], v[162:165], v[196:199], v[14:17]
	v_mfma_f32_16x16x32_bf16 v[6:9], v[154:157], v[200:203], v[6:9]
	v_mfma_f32_16x16x32_bf16 v[6:9], v[162:165], v[232:235], v[6:9]
	v_mfma_f32_16x16x32_bf16 v[18:21], v[146:149], v[200:203], v[18:21]
	v_mfma_f32_16x16x32_bf16 v[18:21], v[150:153], v[232:235], v[18:21]
	v_mfma_f32_16x16x32_bf16 v[26:29], v[146:149], v[192:195], v[26:29]
	v_mfma_f32_16x16x32_bf16 v[26:29], v[150:153], v[196:199], v[26:29]
	v_mfma_f32_16x16x32_bf16 v[54:57], v[146:149], v[184:187], v[54:57]
	v_mfma_f32_16x16x32_bf16 v[54:57], v[150:153], v[188:191], v[54:57]
	v_mfma_f32_16x16x32_bf16 v[78:81], v[146:149], v[166:169], v[78:81]
	v_mfma_f32_16x16x32_bf16 v[78:81], v[150:153], v[170:173], v[78:81]
	v_mfma_f32_16x16x32_bf16 v[50:53], v[138:141], v[166:169], v[50:53]
	v_mfma_f32_16x16x32_bf16 v[50:53], v[142:145], v[170:173], v[50:53]
	v_mfma_f32_16x16x32_bf16 v[30:33], v[138:141], v[184:187], v[30:33]
	v_mfma_f32_16x16x32_bf16 v[30:33], v[142:145], v[188:191], v[30:33]
	v_mfma_f32_16x16x32_bf16 v[10:13], v[138:141], v[192:195], v[10:13]
	v_mfma_f32_16x16x32_bf16 v[10:13], v[142:145], v[196:199], v[10:13]
	v_mfma_f32_16x16x32_bf16 v[2:5], v[138:141], v[200:203], v[2:5]
	v_mfma_f32_16x16x32_bf16 v[2:5], v[142:145], v[232:235], v[2:5]
	v_mfma_f32_16x16x32_bf16 v[22:25], v[130:133], v[200:203], v[22:25]
	v_mfma_f32_16x16x32_bf16 v[22:25], v[134:137], v[232:235], v[22:25]
	v_mfma_f32_16x16x32_bf16 v[46:49], v[130:133], v[192:195], v[46:49]
	v_mfma_f32_16x16x32_bf16 v[46:49], v[134:137], v[196:199], v[46:49]
	v_mfma_f32_16x16x32_bf16 v[62:65], v[130:133], v[184:187], v[62:65]
	v_mfma_f32_16x16x32_bf16 v[62:65], v[134:137], v[188:191], v[62:65]
	v_mfma_f32_16x16x32_bf16 v[94:97], v[130:133], v[166:169], v[94:97]
	v_mfma_f32_16x16x32_bf16 v[94:97], v[134:137], v[170:173], v[94:97]
	s_setprio 0
	s_barrier
	s_add_i32 s69, 0, 0x18000
	s_add_i32 s70, 0, 0x1c000
	v_add_u32_e32 v142, s69, v205
	v_add_u32_e32 v162, s70, v205
	ds_read_b128 v[130:133], v142
	ds_read_b128 v[134:137], v142 offset:1024
	ds_read_b128 v[138:141], v142 offset:2048
	ds_read_b128 v[142:145], v142 offset:3072
	ds_read_b128 v[146:149], v162
	ds_read_b128 v[150:153], v162 offset:1024
	ds_read_b128 v[154:157], v162 offset:2048
	ds_read_b128 v[162:165], v162 offset:3072
	s_add_u32 s26, s26, 0x80000
	s_addc_u32 s27, s27, 0
	s_mov_b32 m0, s56
	ds_read_b128 v[166:169], v230 offset:32768
	ds_read_b128 v[170:173], v230 offset:33792
	ds_read_b128 v[184:187], v230 offset:34816
	ds_read_b128 v[188:191], v230 offset:35840
	ds_read_b128 v[192:195], v230 offset:36864
	ds_read_b128 v[196:199], v230 offset:37888
	ds_read_b128 v[200:203], v230 offset:38912
	ds_read_b128 v[232:235], v230 offset:39936
	global_load_lds_dwordx4 v174, s[26:27]
	s_mov_b32 m0, s57
	s_nop 0
	global_load_lds_dwordx4 v160, s[26:27]
	s_waitcnt vmcnt(8)
	s_waitcnt lgkmcnt(0)
	s_barrier
	s_setprio 1
	s_waitcnt lgkmcnt(0)
	v_mfma_f32_16x16x32_bf16 v[126:129], v[130:133], v[166:169], v[126:129]
	v_mfma_f32_16x16x32_bf16 v[126:129], v[134:137], v[170:173], v[126:129]
	v_mfma_f32_16x16x32_bf16 v[118:121], v[130:133], v[184:187], v[118:121]
	v_mfma_f32_16x16x32_bf16 v[118:121], v[134:137], v[188:191], v[118:121]
	v_mfma_f32_16x16x32_bf16 v[110:113], v[130:133], v[192:195], v[110:113]
	v_mfma_f32_16x16x32_bf16 v[110:113], v[134:137], v[196:199], v[110:113]
	v_mfma_f32_16x16x32_bf16 v[102:105], v[130:133], v[200:203], v[102:105]
	v_mfma_f32_16x16x32_bf16 v[102:105], v[134:137], v[232:235], v[102:105]
	v_mfma_f32_16x16x32_bf16 v[38:41], v[138:141], v[200:203], v[38:41]
	v_mfma_f32_16x16x32_bf16 v[38:41], v[142:145], v[232:235], v[38:41]
	v_mfma_f32_16x16x32_bf16 v[66:69], v[138:141], v[192:195], v[66:69]
	v_mfma_f32_16x16x32_bf16 v[66:69], v[142:145], v[196:199], v[66:69]
	v_mfma_f32_16x16x32_bf16 v[86:89], v[138:141], v[184:187], v[86:89]
	v_mfma_f32_16x16x32_bf16 v[86:89], v[142:145], v[188:191], v[86:89]
	v_mfma_f32_16x16x32_bf16 v[74:77], v[138:141], v[166:169], v[74:77]
	v_mfma_f32_16x16x32_bf16 v[74:77], v[142:145], v[170:173], v[74:77]
	v_mfma_f32_16x16x32_bf16 v[122:125], v[146:149], v[166:169], v[122:125]
	v_mfma_f32_16x16x32_bf16 v[122:125], v[150:153], v[170:173], v[122:125]
	v_mfma_f32_16x16x32_bf16 v[114:117], v[146:149], v[184:187], v[114:117]
	v_mfma_f32_16x16x32_bf16 v[114:117], v[150:153], v[188:191], v[114:117]
	v_mfma_f32_16x16x32_bf16 v[106:109], v[146:149], v[192:195], v[106:109]
	v_mfma_f32_16x16x32_bf16 v[106:109], v[150:153], v[196:199], v[106:109]
	v_mfma_f32_16x16x32_bf16 v[98:101], v[146:149], v[200:203], v[98:101]
	v_mfma_f32_16x16x32_bf16 v[98:101], v[150:153], v[232:235], v[98:101]
	v_mfma_f32_16x16x32_bf16 v[42:45], v[154:157], v[200:203], v[42:45]
	v_mfma_f32_16x16x32_bf16 v[42:45], v[162:165], v[232:235], v[42:45]
	v_mfma_f32_16x16x32_bf16 v[70:73], v[154:157], v[192:195], v[70:73]
	v_mfma_f32_16x16x32_bf16 v[70:73], v[162:165], v[196:199], v[70:73]
	v_mfma_f32_16x16x32_bf16 v[90:93], v[154:157], v[184:187], v[90:93]
	v_mfma_f32_16x16x32_bf16 v[90:93], v[162:165], v[188:191], v[90:93]
	v_mfma_f32_16x16x32_bf16 v[82:85], v[154:157], v[166:169], v[82:85]
	v_mfma_f32_16x16x32_bf16 v[82:85], v[162:165], v[170:173], v[82:85]
	s_setprio 0
	s_barrier
	s_add_i32 s26, s69, s33
	v_lshl_add_u64 v[212:213], v[212:213], 0, s[30:31]
	s_mov_b32 m0, s26
	ds_read_b128 v[166:169], v230 offset:49152
	ds_read_b128 v[170:173], v230 offset:50176
	ds_read_b128 v[184:187], v230 offset:51200
	ds_read_b128 v[188:191], v230 offset:52224
	ds_read_b128 v[192:195], v230 offset:53248
	ds_read_b128 v[196:199], v230 offset:54272
	ds_read_b128 v[200:203], v230 offset:55296
	ds_read_b128 v[232:235], v230 offset:56320
	global_load_lds_dwordx4 v[212:213], off
	s_add_i32 m0, s26, 0x2000
	s_add_u32 s22, s22, 0x80080
	v_lshl_add_u64 v[212:213], v[220:221], 0, s[30:31]
	s_addc_u32 s23, s23, 0
	s_add_i32 s26, s70, s33
	global_load_lds_dwordx4 v[212:213], off
	s_mov_b32 m0, s26
	s_nop 0
	global_load_lds_dwordx4 v0, s[22:23]
	s_add_i32 m0, s26, 0x2000
	s_nop 0
	global_load_lds_dwordx4 v158, s[22:23]
	v_lshl_add_u64 v[212:213], v[236:237], 0, s[30:31]
	s_mov_b32 m0, s59
	s_nop 0
	global_load_lds_dwordx4 v[212:213], off
	v_lshl_add_u64 v[212:213], v[238:239], 0, s[30:31]
	s_mov_b32 m0, s60
	s_nop 0
	global_load_lds_dwordx4 v[212:213], off
	s_waitcnt vmcnt(8)
	s_waitcnt lgkmcnt(0)
	s_barrier
	s_setprio 1
	s_waitcnt lgkmcnt(0)
	v_mfma_f32_16x16x32_bf16 v[58:61], v[154:157], v[166:169], v[58:61]
	v_mfma_f32_16x16x32_bf16 v[58:61], v[162:165], v[170:173], v[58:61]
	v_mfma_f32_16x16x32_bf16 v[34:37], v[154:157], v[184:187], v[34:37]
	v_mfma_f32_16x16x32_bf16 v[34:37], v[162:165], v[188:191], v[34:37]
	v_mfma_f32_16x16x32_bf16 v[14:17], v[154:157], v[192:195], v[14:17]
	v_mfma_f32_16x16x32_bf16 v[14:17], v[162:165], v[196:199], v[14:17]
	v_mfma_f32_16x16x32_bf16 v[6:9], v[154:157], v[200:203], v[6:9]
	v_mfma_f32_16x16x32_bf16 v[6:9], v[162:165], v[232:235], v[6:9]
	v_mfma_f32_16x16x32_bf16 v[18:21], v[146:149], v[200:203], v[18:21]
	v_mfma_f32_16x16x32_bf16 v[18:21], v[150:153], v[232:235], v[18:21]
	v_mfma_f32_16x16x32_bf16 v[26:29], v[146:149], v[192:195], v[26:29]
	v_mfma_f32_16x16x32_bf16 v[26:29], v[150:153], v[196:199], v[26:29]
	v_mfma_f32_16x16x32_bf16 v[54:57], v[146:149], v[184:187], v[54:57]
	v_mfma_f32_16x16x32_bf16 v[54:57], v[150:153], v[188:191], v[54:57]
	v_mfma_f32_16x16x32_bf16 v[78:81], v[146:149], v[166:169], v[78:81]
	v_mfma_f32_16x16x32_bf16 v[78:81], v[150:153], v[170:173], v[78:81]
	v_mfma_f32_16x16x32_bf16 v[50:53], v[138:141], v[166:169], v[50:53]
	v_mfma_f32_16x16x32_bf16 v[50:53], v[142:145], v[170:173], v[50:53]
	v_mfma_f32_16x16x32_bf16 v[30:33], v[138:141], v[184:187], v[30:33]
	v_mfma_f32_16x16x32_bf16 v[30:33], v[142:145], v[188:191], v[30:33]
	v_mfma_f32_16x16x32_bf16 v[10:13], v[138:141], v[192:195], v[10:13]
	v_mfma_f32_16x16x32_bf16 v[10:13], v[142:145], v[196:199], v[10:13]
	v_mfma_f32_16x16x32_bf16 v[2:5], v[138:141], v[200:203], v[2:5]
	v_mfma_f32_16x16x32_bf16 v[2:5], v[142:145], v[232:235], v[2:5]
	v_mfma_f32_16x16x32_bf16 v[22:25], v[130:133], v[200:203], v[22:25]
	v_mfma_f32_16x16x32_bf16 v[22:25], v[134:137], v[232:235], v[22:25]
	v_mfma_f32_16x16x32_bf16 v[46:49], v[130:133], v[192:195], v[46:49]
	v_mfma_f32_16x16x32_bf16 v[46:49], v[134:137], v[196:199], v[46:49]
	v_mfma_f32_16x16x32_bf16 v[62:65], v[130:133], v[184:187], v[62:65]
	v_mfma_f32_16x16x32_bf16 v[62:65], v[134:137], v[188:191], v[62:65]
	v_mfma_f32_16x16x32_bf16 v[94:97], v[130:133], v[166:169], v[94:97]
	v_mfma_f32_16x16x32_bf16 v[94:97], v[134:137], v[170:173], v[94:97]
	s_setprio 0
	s_barrier
	s_add_i32 s25, s25, 2
	s_add_u32 s16, s16, 0x100
	s_addc_u32 s17, s17, 0
	s_add_u32 s21, s21, 0x100
	s_addc_u32 s24, s24, 0
	s_cmp_gt_u32 s25, 29
	s_cbranch_scc0 .LBB0_1997
	v_readlane_b32 s16, v253, 2
	v_readlane_b32 s17, v253, 3
	s_and_b64 vcc, exec, s[16:17]
	s_cbranch_vccz .LBB0_2000
	s_barrier

.LBB0_2111:
	s_add_u32 s16, s14, 0xfffc0080
	s_addc_u32 s17, s15, -1
	s_add_i32 s51, 0, 0x10000
	s_cmp_eq_u32 s50, 12
	s_cselect_b32 s21, s9, s17
	s_cselect_b32 s20, s46, s16
	s_cselect_b32 s17, s5, s49
	s_cselect_b32 s16, s47, s48
	s_add_i32 s54, 0, 0x14000
	v_add_u32_e32 v154, s51, v181
	v_add_u32_e32 v170, s54, v181
	ds_read_b128 v[130:133], v154
	ds_read_b128 v[134:137], v154 offset:1024
	ds_read_b128 v[150:153], v154 offset:2048
	ds_read_b128 v[154:157], v154 offset:3072
	ds_read_b128 v[158:161], v170
	ds_read_b128 v[162:165], v170 offset:1024
	ds_read_b128 v[166:169], v170 offset:2048
	ds_read_b128 v[170:173], v170 offset:3072
	s_add_i32 m0, s26, 0xc000
	ds_read_b128 v[174:177], v184
	ds_read_b128 v[186:189], v184 offset:1024
	ds_read_b128 v[190:193], v184 offset:2048
	ds_read_b128 v[194:197], v184 offset:3072
	ds_read_b128 v[198:201], v184 offset:4096
	ds_read_b128 v[202:205], v184 offset:5120
	ds_read_b128 v[206:209], v184 offset:6144
	ds_read_b128 v[210:213], v184 offset:7168
	global_load_lds_dwordx4 v146, s[14:15]
	s_add_i32 m0, s26, 0xe000
	s_nop 0
	global_load_lds_dwordx4 v148, s[14:15]
	s_waitcnt vmcnt(8)
	s_waitcnt lgkmcnt(0)
	s_barrier
	s_setprio 1
	s_waitcnt lgkmcnt(0)
	v_mfma_i32_16x16x64_i8 v[126:129], v[130:133], v[174:177], v[126:129]
	v_mfma_i32_16x16x64_i8 v[126:129], v[134:137], v[186:189], v[126:129]
	v_mfma_i32_16x16x64_i8 v[110:113], v[130:133], v[190:193], v[110:113]
	v_mfma_i32_16x16x64_i8 v[110:113], v[134:137], v[194:197], v[110:113]
	v_mfma_i32_16x16x64_i8 v[94:97], v[130:133], v[198:201], v[94:97]
	v_mfma_i32_16x16x64_i8 v[94:97], v[134:137], v[202:205], v[94:97]
	v_mfma_i32_16x16x64_i8 v[78:81], v[130:133], v[206:209], v[78:81]
	v_mfma_i32_16x16x64_i8 v[78:81], v[134:137], v[210:213], v[78:81]
	v_mfma_i32_16x16x64_i8 v[70:73], v[150:153], v[206:209], v[70:73]
	v_mfma_i32_16x16x64_i8 v[70:73], v[154:157], v[210:213], v[70:73]
	v_mfma_i32_16x16x64_i8 v[86:89], v[150:153], v[198:201], v[86:89]
	v_mfma_i32_16x16x64_i8 v[86:89], v[154:157], v[202:205], v[86:89]
	v_mfma_i32_16x16x64_i8 v[102:105], v[150:153], v[190:193], v[102:105]
	v_mfma_i32_16x16x64_i8 v[102:105], v[154:157], v[194:197], v[102:105]
	v_mfma_i32_16x16x64_i8 v[122:125], v[150:153], v[174:177], v[122:125]
	v_mfma_i32_16x16x64_i8 v[122:125], v[154:157], v[186:189], v[122:125]
	v_mfma_i32_16x16x64_i8 v[118:121], v[158:161], v[174:177], v[118:121]
	v_mfma_i32_16x16x64_i8 v[118:121], v[162:165], v[186:189], v[118:121]
	v_mfma_i32_16x16x64_i8 v[106:109], v[158:161], v[190:193], v[106:109]
	v_mfma_i32_16x16x64_i8 v[106:109], v[162:165], v[194:197], v[106:109]
	v_mfma_i32_16x16x64_i8 v[90:93], v[158:161], v[198:201], v[90:93]
	v_mfma_i32_16x16x64_i8 v[90:93], v[162:165], v[202:205], v[90:93]
	v_mfma_i32_16x16x64_i8 v[74:77], v[158:161], v[206:209], v[74:77]
	v_mfma_i32_16x16x64_i8 v[74:77], v[162:165], v[210:213], v[74:77]
	v_mfma_i32_16x16x64_i8 v[66:69], v[166:169], v[206:209], v[66:69]
	v_mfma_i32_16x16x64_i8 v[66:69], v[170:173], v[210:213], v[66:69]
	v_mfma_i32_16x16x64_i8 v[82:85], v[166:169], v[198:201], v[82:85]
	v_mfma_i32_16x16x64_i8 v[82:85], v[170:173], v[202:205], v[82:85]
	v_mfma_i32_16x16x64_i8 v[98:101], v[166:169], v[190:193], v[98:101]
	v_mfma_i32_16x16x64_i8 v[98:101], v[170:173], v[194:197], v[98:101]
	v_mfma_i32_16x16x64_i8 v[114:117], v[166:169], v[174:177], v[114:117]
	v_mfma_i32_16x16x64_i8 v[114:117], v[170:173], v[186:189], v[114:117]
	s_setprio 0
	s_barrier
	s_add_i32 s51, s51, s33
	v_lshl_add_u64 v[178:179], s[16:17], 0, v[0:1]
	s_mov_b32 m0, s51
	ds_read_b128 v[174:177], v184 offset:16384
	ds_read_b128 v[186:189], v184 offset:17408
	ds_read_b128 v[190:193], v184 offset:18432
	ds_read_b128 v[194:197], v184 offset:19456
	ds_read_b128 v[198:201], v184 offset:20480
	ds_read_b128 v[202:205], v184 offset:21504
	ds_read_b128 v[206:209], v184 offset:22528
	ds_read_b128 v[210:213], v184 offset:23552
	global_load_lds_dwordx4 v[178:179], off
	s_add_i32 m0, s51, 0x2000
	s_add_u32 s52, s16, 0x40000
	v_lshl_add_u64 v[220:221], s[16:17], 0, v[138:139]
	s_addc_u32 s53, s17, 0
	s_add_i32 s51, s54, s33
	global_load_lds_dwordx4 v[220:221], off
	s_mov_b32 m0, s51
	v_lshl_add_u64 v[226:227], s[20:21], 0, v[140:141]
	global_load_lds_dwordx4 v0, s[52:53]
	s_add_i32 m0, s51, 0x2000
	s_nop 0
	global_load_lds_dwordx4 v138, s[52:53]
	v_lshl_add_u64 v[224:225], s[20:21], 0, v[142:143]
	s_mov_b32 m0, s26
	s_nop 0
	global_load_lds_dwordx4 v[224:225], off
	s_mov_b32 m0, s27
	s_nop 0
	global_load_lds_dwordx4 v[226:227], off
	s_waitcnt vmcnt(8)
	s_waitcnt lgkmcnt(0)
	s_barrier
	s_setprio 1
	s_waitcnt lgkmcnt(0)
	v_mfma_i32_16x16x64_i8 v[50:53], v[166:169], v[174:177], v[50:53]
	v_mfma_i32_16x16x64_i8 v[50:53], v[170:173], v[186:189], v[50:53]
	v_mfma_i32_16x16x64_i8 v[34:37], v[166:169], v[190:193], v[34:37]
	v_mfma_i32_16x16x64_i8 v[34:37], v[170:173], v[194:197], v[34:37]
	v_mfma_i32_16x16x64_i8 v[18:21], v[166:169], v[198:201], v[18:21]
	v_mfma_i32_16x16x64_i8 v[18:21], v[170:173], v[202:205], v[18:21]
	v_mfma_i32_16x16x64_i8 v[2:5], v[166:169], v[206:209], v[2:5]
	v_mfma_i32_16x16x64_i8 v[2:5], v[170:173], v[210:213], v[2:5]
	v_mfma_i32_16x16x64_i8 v[10:13], v[158:161], v[206:209], v[10:13]
	v_mfma_i32_16x16x64_i8 v[10:13], v[162:165], v[210:213], v[10:13]
	v_mfma_i32_16x16x64_i8 v[26:29], v[158:161], v[198:201], v[26:29]
	v_mfma_i32_16x16x64_i8 v[26:29], v[162:165], v[202:205], v[26:29]
	v_mfma_i32_16x16x64_i8 v[42:45], v[158:161], v[190:193], v[42:45]
	v_mfma_i32_16x16x64_i8 v[42:45], v[162:165], v[194:197], v[42:45]
	v_mfma_i32_16x16x64_i8 v[58:61], v[158:161], v[174:177], v[58:61]
	v_mfma_i32_16x16x64_i8 v[58:61], v[162:165], v[186:189], v[58:61]
	v_mfma_i32_16x16x64_i8 v[54:57], v[150:153], v[174:177], v[54:57]
	v_mfma_i32_16x16x64_i8 v[54:57], v[154:157], v[186:189], v[54:57]
	v_mfma_i32_16x16x64_i8 v[38:41], v[150:153], v[190:193], v[38:41]
	v_mfma_i32_16x16x64_i8 v[38:41], v[154:157], v[194:197], v[38:41]
	v_mfma_i32_16x16x64_i8 v[22:25], v[150:153], v[198:201], v[22:25]
	v_mfma_i32_16x16x64_i8 v[22:25], v[154:157], v[202:205], v[22:25]
	v_mfma_i32_16x16x64_i8 v[6:9], v[150:153], v[206:209], v[6:9]
	v_mfma_i32_16x16x64_i8 v[6:9], v[154:157], v[210:213], v[6:9]
	v_mfma_i32_16x16x64_i8 v[14:17], v[130:133], v[206:209], v[14:17]
	v_mfma_i32_16x16x64_i8 v[14:17], v[134:137], v[210:213], v[14:17]
	v_mfma_i32_16x16x64_i8 v[30:33], v[130:133], v[198:201], v[30:33]
	v_mfma_i32_16x16x64_i8 v[30:33], v[134:137], v[202:205], v[30:33]
	v_mfma_i32_16x16x64_i8 v[46:49], v[130:133], v[190:193], v[46:49]
	v_mfma_i32_16x16x64_i8 v[46:49], v[134:137], v[194:197], v[46:49]
	v_mfma_i32_16x16x64_i8 v[62:65], v[130:133], v[174:177], v[62:65]
	v_mfma_i32_16x16x64_i8 v[62:65], v[134:137], v[186:189], v[62:65]
	s_setprio 0
	s_barrier
	s_add_i32 s51, 0, 0x18000
	s_add_i32 s52, 0, 0x1c000
	v_add_u32_e32 v154, s51, v181
	v_add_u32_e32 v170, s52, v181
	ds_read_b128 v[130:133], v154
	ds_read_b128 v[134:137], v154 offset:1024
	ds_read_b128 v[150:153], v154 offset:2048
	ds_read_b128 v[154:157], v154 offset:3072
	ds_read_b128 v[158:161], v170
	ds_read_b128 v[162:165], v170 offset:1024
	ds_read_b128 v[166:169], v170 offset:2048
	ds_read_b128 v[170:173], v170 offset:3072
	s_add_u32 s20, s20, 0x40000
	s_addc_u32 s21, s21, 0
	s_mov_b32 m0, s28
	ds_read_b128 v[174:177], v184 offset:32768
	ds_read_b128 v[186:189], v184 offset:33792
	ds_read_b128 v[190:193], v184 offset:34816
	ds_read_b128 v[194:197], v184 offset:35840
	ds_read_b128 v[198:201], v184 offset:36864
	ds_read_b128 v[202:205], v184 offset:37888
	ds_read_b128 v[206:209], v184 offset:38912
	ds_read_b128 v[210:213], v184 offset:39936
	global_load_lds_dwordx4 v142, s[20:21]
	s_mov_b32 m0, s29
	s_nop 0
	global_load_lds_dwordx4 v140, s[20:21]
	s_waitcnt vmcnt(8)
	s_waitcnt lgkmcnt(0)
	s_barrier
	s_setprio 1
	s_waitcnt lgkmcnt(0)
	v_mfma_i32_16x16x64_i8 v[126:129], v[130:133], v[174:177], v[126:129]
	v_mfma_i32_16x16x64_i8 v[126:129], v[134:137], v[186:189], v[126:129]
	v_mfma_i32_16x16x64_i8 v[110:113], v[130:133], v[190:193], v[110:113]
	v_mfma_i32_16x16x64_i8 v[110:113], v[134:137], v[194:197], v[110:113]
	v_mfma_i32_16x16x64_i8 v[94:97], v[130:133], v[198:201], v[94:97]
	v_mfma_i32_16x16x64_i8 v[94:97], v[134:137], v[202:205], v[94:97]
	v_mfma_i32_16x16x64_i8 v[78:81], v[130:133], v[206:209], v[78:81]
	v_mfma_i32_16x16x64_i8 v[78:81], v[134:137], v[210:213], v[78:81]
	v_mfma_i32_16x16x64_i8 v[70:73], v[150:153], v[206:209], v[70:73]
	v_mfma_i32_16x16x64_i8 v[70:73], v[154:157], v[210:213], v[70:73]
	v_mfma_i32_16x16x64_i8 v[86:89], v[150:153], v[198:201], v[86:89]
	v_mfma_i32_16x16x64_i8 v[86:89], v[154:157], v[202:205], v[86:89]
	v_mfma_i32_16x16x64_i8 v[102:105], v[150:153], v[190:193], v[102:105]
	v_mfma_i32_16x16x64_i8 v[102:105], v[154:157], v[194:197], v[102:105]
	v_mfma_i32_16x16x64_i8 v[122:125], v[150:153], v[174:177], v[122:125]
	v_mfma_i32_16x16x64_i8 v[122:125], v[154:157], v[186:189], v[122:125]
	v_mfma_i32_16x16x64_i8 v[118:121], v[158:161], v[174:177], v[118:121]
	v_mfma_i32_16x16x64_i8 v[118:121], v[162:165], v[186:189], v[118:121]
	v_mfma_i32_16x16x64_i8 v[106:109], v[158:161], v[190:193], v[106:109]
	v_mfma_i32_16x16x64_i8 v[106:109], v[162:165], v[194:197], v[106:109]
	v_mfma_i32_16x16x64_i8 v[90:93], v[158:161], v[198:201], v[90:93]
	v_mfma_i32_16x16x64_i8 v[90:93], v[162:165], v[202:205], v[90:93]
	v_mfma_i32_16x16x64_i8 v[74:77], v[158:161], v[206:209], v[74:77]
	v_mfma_i32_16x16x64_i8 v[74:77], v[162:165], v[210:213], v[74:77]
	v_mfma_i32_16x16x64_i8 v[66:69], v[166:169], v[206:209], v[66:69]
	v_mfma_i32_16x16x64_i8 v[66:69], v[170:173], v[210:213], v[66:69]
	v_mfma_i32_16x16x64_i8 v[82:85], v[166:169], v[198:201], v[82:85]
	v_mfma_i32_16x16x64_i8 v[82:85], v[170:173], v[202:205], v[82:85]
	v_mfma_i32_16x16x64_i8 v[98:101], v[166:169], v[190:193], v[98:101]
	v_mfma_i32_16x16x64_i8 v[98:101], v[170:173], v[194:197], v[98:101]
	v_mfma_i32_16x16x64_i8 v[114:117], v[166:169], v[174:177], v[114:117]
	v_mfma_i32_16x16x64_i8 v[114:117], v[170:173], v[186:189], v[114:117]
	s_setprio 0
	s_barrier
	s_add_i32 s20, s51, s33
	v_lshl_add_u64 v[178:179], v[178:179], 0, s[30:31]
	s_mov_b32 m0, s20
	ds_read_b128 v[174:177], v184 offset:49152
	ds_read_b128 v[186:189], v184 offset:50176
	ds_read_b128 v[190:193], v184 offset:51200
	ds_read_b128 v[194:197], v184 offset:52224
	ds_read_b128 v[198:201], v184 offset:53248
	ds_read_b128 v[202:205], v184 offset:54272
	ds_read_b128 v[206:209], v184 offset:55296
	ds_read_b128 v[210:213], v184 offset:56320
	global_load_lds_dwordx4 v[178:179], off
	s_add_i32 m0, s20, 0x2000
	s_add_u32 s16, s16, 0x40080
	v_lshl_add_u64 v[178:179], v[220:221], 0, s[30:31]
	s_addc_u32 s17, s17, 0
	s_add_i32 s20, s52, s33
	global_load_lds_dwordx4 v[178:179], off
	s_mov_b32 m0, s20
	s_nop 0
	global_load_lds_dwordx4 v0, s[16:17]
	s_add_i32 m0, s20, 0x2000
	s_nop 0
	global_load_lds_dwordx4 v138, s[16:17]
	v_lshl_add_u64 v[178:179], v[224:225], 0, s[30:31]
	s_mov_b32 m0, s34
	s_nop 0
	global_load_lds_dwordx4 v[178:179], off
	v_lshl_add_u64 v[178:179], v[226:227], 0, s[30:31]
	s_mov_b32 m0, s35
	s_nop 0
	global_load_lds_dwordx4 v[178:179], off
	s_waitcnt vmcnt(8)
	s_waitcnt lgkmcnt(0)
	s_barrier
	s_setprio 1
	s_waitcnt lgkmcnt(0)
	v_mfma_i32_16x16x64_i8 v[50:53], v[166:169], v[174:177], v[50:53]
	v_mfma_i32_16x16x64_i8 v[50:53], v[170:173], v[186:189], v[50:53]
	v_mfma_i32_16x16x64_i8 v[34:37], v[166:169], v[190:193], v[34:37]
	v_mfma_i32_16x16x64_i8 v[34:37], v[170:173], v[194:197], v[34:37]
	v_mfma_i32_16x16x64_i8 v[18:21], v[166:169], v[198:201], v[18:21]
	v_mfma_i32_16x16x64_i8 v[18:21], v[170:173], v[202:205], v[18:21]
	v_mfma_i32_16x16x64_i8 v[2:5], v[166:169], v[206:209], v[2:5]
	v_mfma_i32_16x16x64_i8 v[2:5], v[170:173], v[210:213], v[2:5]
	v_mfma_i32_16x16x64_i8 v[10:13], v[158:161], v[206:209], v[10:13]
	v_mfma_i32_16x16x64_i8 v[10:13], v[162:165], v[210:213], v[10:13]
	v_mfma_i32_16x16x64_i8 v[26:29], v[158:161], v[198:201], v[26:29]
	v_mfma_i32_16x16x64_i8 v[26:29], v[162:165], v[202:205], v[26:29]
	v_mfma_i32_16x16x64_i8 v[42:45], v[158:161], v[190:193], v[42:45]
	v_mfma_i32_16x16x64_i8 v[42:45], v[162:165], v[194:197], v[42:45]
	v_mfma_i32_16x16x64_i8 v[58:61], v[158:161], v[174:177], v[58:61]
	v_mfma_i32_16x16x64_i8 v[58:61], v[162:165], v[186:189], v[58:61]
	v_mfma_i32_16x16x64_i8 v[54:57], v[150:153], v[174:177], v[54:57]
	v_mfma_i32_16x16x64_i8 v[54:57], v[154:157], v[186:189], v[54:57]
	v_mfma_i32_16x16x64_i8 v[38:41], v[150:153], v[190:193], v[38:41]
	v_mfma_i32_16x16x64_i8 v[38:41], v[154:157], v[194:197], v[38:41]
	v_mfma_i32_16x16x64_i8 v[22:25], v[150:153], v[198:201], v[22:25]
	v_mfma_i32_16x16x64_i8 v[22:25], v[154:157], v[202:205], v[22:25]
	v_mfma_i32_16x16x64_i8 v[6:9], v[150:153], v[206:209], v[6:9]
	v_mfma_i32_16x16x64_i8 v[6:9], v[154:157], v[210:213], v[6:9]
	v_mfma_i32_16x16x64_i8 v[14:17], v[130:133], v[206:209], v[14:17]
	v_mfma_i32_16x16x64_i8 v[14:17], v[134:137], v[210:213], v[14:17]
	v_mfma_i32_16x16x64_i8 v[30:33], v[130:133], v[198:201], v[30:33]
	v_mfma_i32_16x16x64_i8 v[30:33], v[134:137], v[202:205], v[30:33]
	v_mfma_i32_16x16x64_i8 v[46:49], v[130:133], v[190:193], v[46:49]
	v_mfma_i32_16x16x64_i8 v[46:49], v[134:137], v[194:197], v[46:49]
	v_mfma_i32_16x16x64_i8 v[62:65], v[130:133], v[174:177], v[62:65]
	v_mfma_i32_16x16x64_i8 v[62:65], v[134:137], v[186:189], v[62:65]
	s_setprio 0
	s_barrier
	s_add_i32 s50, s50, 2
	s_add_u32 s14, s14, 0x100
	s_addc_u32 s15, s15, 0
	s_add_u32 s48, s48, 0x100
	s_addc_u32 s49, s49, 0
	s_cmp_gt_u32 s50, 13
	s_cbranch_scc0 .LBB0_2111
	v_readlane_b32 s14, v253, 2
	v_readlane_b32 s15, v253, 3
	s_and_b64 vcc, exec, s[14:15]
	s_cbranch_vccz .LBB0_2114
	s_barrier

.LBB0_2193:
	s_add_u32 s16, s12, 0x100
	s_addc_u32 s17, s13, 0
	s_add_i32 s67, 0, 0x10000
	s_cmpk_eq_i32 s19, 0x54
	s_cselect_b32 s23, s7, s17
	s_cselect_b32 s22, s6, s16
	s_cselect_b32 s21, s11, s18
	s_cselect_b32 s20, s10, s15
	s_add_i32 s68, 0, 0x14000
	v_add_u32_e32 v142, s67, v205
	v_add_u32_e32 v162, s68, v205
	ds_read_b128 v[130:133], v142
	ds_read_b128 v[134:137], v142 offset:1024
	ds_read_b128 v[138:141], v142 offset:2048
	ds_read_b128 v[142:145], v142 offset:3072
	ds_read_b128 v[146:149], v162
	ds_read_b128 v[150:153], v162 offset:1024
	ds_read_b128 v[154:157], v162 offset:2048
	ds_read_b128 v[162:165], v162 offset:3072
	s_add_i32 m0, s28, 0xc000
	ds_read_b128 v[166:169], v230
	ds_read_b128 v[170:173], v230 offset:1024
	ds_read_b128 v[184:187], v230 offset:2048
	ds_read_b128 v[188:191], v230 offset:3072
	ds_read_b128 v[192:195], v230 offset:4096
	ds_read_b128 v[196:199], v230 offset:5120
	ds_read_b128 v[200:203], v230 offset:6144
	ds_read_b128 v[232:235], v230 offset:7168
	global_load_lds_dwordx4 v180, s[12:13]
	s_add_i32 m0, s28, 0xe000
	s_nop 0
	global_load_lds_dwordx4 v182, s[12:13]
	s_waitcnt vmcnt(8)
	s_waitcnt lgkmcnt(0)
	s_barrier
	s_setprio 1
	s_waitcnt lgkmcnt(0)
	v_mfma_f32_16x16x32_bf16 v[126:129], v[130:133], v[166:169], v[126:129]
	v_mfma_f32_16x16x32_bf16 v[126:129], v[134:137], v[170:173], v[126:129]
	v_mfma_f32_16x16x32_bf16 v[118:121], v[130:133], v[184:187], v[118:121]
	v_mfma_f32_16x16x32_bf16 v[118:121], v[134:137], v[188:191], v[118:121]
	v_mfma_f32_16x16x32_bf16 v[110:113], v[130:133], v[192:195], v[110:113]
	v_mfma_f32_16x16x32_bf16 v[110:113], v[134:137], v[196:199], v[110:113]
	v_mfma_f32_16x16x32_bf16 v[102:105], v[130:133], v[200:203], v[102:105]
	v_mfma_f32_16x16x32_bf16 v[102:105], v[134:137], v[232:235], v[102:105]
	v_mfma_f32_16x16x32_bf16 v[38:41], v[138:141], v[200:203], v[38:41]
	v_mfma_f32_16x16x32_bf16 v[38:41], v[142:145], v[232:235], v[38:41]
	v_mfma_f32_16x16x32_bf16 v[66:69], v[138:141], v[192:195], v[66:69]
	v_mfma_f32_16x16x32_bf16 v[66:69], v[142:145], v[196:199], v[66:69]
	v_mfma_f32_16x16x32_bf16 v[86:89], v[138:141], v[184:187], v[86:89]
	v_mfma_f32_16x16x32_bf16 v[86:89], v[142:145], v[188:191], v[86:89]
	v_mfma_f32_16x16x32_bf16 v[74:77], v[138:141], v[166:169], v[74:77]
	v_mfma_f32_16x16x32_bf16 v[74:77], v[142:145], v[170:173], v[74:77]
	v_mfma_f32_16x16x32_bf16 v[122:125], v[146:149], v[166:169], v[122:125]
	v_mfma_f32_16x16x32_bf16 v[122:125], v[150:153], v[170:173], v[122:125]
	v_mfma_f32_16x16x32_bf16 v[114:117], v[146:149], v[184:187], v[114:117]
	v_mfma_f32_16x16x32_bf16 v[114:117], v[150:153], v[188:191], v[114:117]
	v_mfma_f32_16x16x32_bf16 v[106:109], v[146:149], v[192:195], v[106:109]
	v_mfma_f32_16x16x32_bf16 v[106:109], v[150:153], v[196:199], v[106:109]
	v_mfma_f32_16x16x32_bf16 v[98:101], v[146:149], v[200:203], v[98:101]
	v_mfma_f32_16x16x32_bf16 v[98:101], v[150:153], v[232:235], v[98:101]
	v_mfma_f32_16x16x32_bf16 v[42:45], v[154:157], v[200:203], v[42:45]
	v_mfma_f32_16x16x32_bf16 v[42:45], v[162:165], v[232:235], v[42:45]
	v_mfma_f32_16x16x32_bf16 v[70:73], v[154:157], v[192:195], v[70:73]
	v_mfma_f32_16x16x32_bf16 v[70:73], v[162:165], v[196:199], v[70:73]
	v_mfma_f32_16x16x32_bf16 v[90:93], v[154:157], v[184:187], v[90:93]
	v_mfma_f32_16x16x32_bf16 v[90:93], v[162:165], v[188:191], v[90:93]
	v_mfma_f32_16x16x32_bf16 v[82:85], v[154:157], v[166:169], v[82:85]
	v_mfma_f32_16x16x32_bf16 v[82:85], v[162:165], v[170:173], v[82:85]
	s_setprio 0
	s_barrier
	s_add_i32 s12, s67, s33
	v_lshl_add_u64 v[212:213], s[20:21], 0, v[0:1]
	s_mov_b32 m0, s12
	ds_read_b128 v[166:169], v230 offset:16384
	ds_read_b128 v[170:173], v230 offset:17408
	ds_read_b128 v[184:187], v230 offset:18432
	ds_read_b128 v[188:191], v230 offset:19456
	ds_read_b128 v[192:195], v230 offset:20480
	ds_read_b128 v[196:199], v230 offset:21504
	ds_read_b128 v[200:203], v230 offset:22528
	ds_read_b128 v[232:235], v230 offset:23552
	global_load_lds_dwordx4 v[212:213], off
	s_add_i32 m0, s12, 0x2000
	s_add_u32 s12, s20, 0x160000
	v_lshl_add_u64 v[220:221], s[20:21], 0, v[158:159]
	s_addc_u32 s13, s21, 0
	s_add_i32 s67, s68, s33
	global_load_lds_dwordx4 v[220:221], off
	s_mov_b32 m0, s67
	v_lshl_add_u64 v[238:239], s[22:23], 0, v[160:161]
	global_load_lds_dwordx4 v0, s[12:13]
	s_add_i32 m0, s67, 0x2000
	s_nop 0
	global_load_lds_dwordx4 v158, s[12:13]
	v_lshl_add_u64 v[236:237], s[22:23], 0, v[174:175]
	s_mov_b32 m0, s28
	s_nop 0
	global_load_lds_dwordx4 v[236:237], off
	s_mov_b32 m0, s29
	s_nop 0
	global_load_lds_dwordx4 v[238:239], off
	s_waitcnt vmcnt(8)
	s_waitcnt lgkmcnt(0)
	s_barrier
	s_setprio 1
	s_waitcnt lgkmcnt(0)
	v_mfma_f32_16x16x32_bf16 v[58:61], v[154:157], v[166:169], v[58:61]
	v_mfma_f32_16x16x32_bf16 v[58:61], v[162:165], v[170:173], v[58:61]
	v_mfma_f32_16x16x32_bf16 v[34:37], v[154:157], v[184:187], v[34:37]
	v_mfma_f32_16x16x32_bf16 v[34:37], v[162:165], v[188:191], v[34:37]
	v_mfma_f32_16x16x32_bf16 v[14:17], v[154:157], v[192:195], v[14:17]
	v_mfma_f32_16x16x32_bf16 v[14:17], v[162:165], v[196:199], v[14:17]
	v_mfma_f32_16x16x32_bf16 v[6:9], v[154:157], v[200:203], v[6:9]
	v_mfma_f32_16x16x32_bf16 v[6:9], v[162:165], v[232:235], v[6:9]
	v_mfma_f32_16x16x32_bf16 v[18:21], v[146:149], v[200:203], v[18:21]
	v_mfma_f32_16x16x32_bf16 v[18:21], v[150:153], v[232:235], v[18:21]
	v_mfma_f32_16x16x32_bf16 v[26:29], v[146:149], v[192:195], v[26:29]
	v_mfma_f32_16x16x32_bf16 v[26:29], v[150:153], v[196:199], v[26:29]
	v_mfma_f32_16x16x32_bf16 v[54:57], v[146:149], v[184:187], v[54:57]
	v_mfma_f32_16x16x32_bf16 v[54:57], v[150:153], v[188:191], v[54:57]
	v_mfma_f32_16x16x32_bf16 v[78:81], v[146:149], v[166:169], v[78:81]
	v_mfma_f32_16x16x32_bf16 v[78:81], v[150:153], v[170:173], v[78:81]
	v_mfma_f32_16x16x32_bf16 v[50:53], v[138:141], v[166:169], v[50:53]
	v_mfma_f32_16x16x32_bf16 v[50:53], v[142:145], v[170:173], v[50:53]
	v_mfma_f32_16x16x32_bf16 v[30:33], v[138:141], v[184:187], v[30:33]
	v_mfma_f32_16x16x32_bf16 v[30:33], v[142:145], v[188:191], v[30:33]
	v_mfma_f32_16x16x32_bf16 v[10:13], v[138:141], v[192:195], v[10:13]
	v_mfma_f32_16x16x32_bf16 v[10:13], v[142:145], v[196:199], v[10:13]
	v_mfma_f32_16x16x32_bf16 v[2:5], v[138:141], v[200:203], v[2:5]
	v_mfma_f32_16x16x32_bf16 v[2:5], v[142:145], v[232:235], v[2:5]
	v_mfma_f32_16x16x32_bf16 v[22:25], v[130:133], v[200:203], v[22:25]
	v_mfma_f32_16x16x32_bf16 v[22:25], v[134:137], v[232:235], v[22:25]
	v_mfma_f32_16x16x32_bf16 v[46:49], v[130:133], v[192:195], v[46:49]
	v_mfma_f32_16x16x32_bf16 v[46:49], v[134:137], v[196:199], v[46:49]
	v_mfma_f32_16x16x32_bf16 v[62:65], v[130:133], v[184:187], v[62:65]
	v_mfma_f32_16x16x32_bf16 v[62:65], v[134:137], v[188:191], v[62:65]
	v_mfma_f32_16x16x32_bf16 v[94:97], v[130:133], v[166:169], v[94:97]
	v_mfma_f32_16x16x32_bf16 v[94:97], v[134:137], v[170:173], v[94:97]
	s_setprio 0
	s_barrier
	s_add_i32 s67, 0, 0x18000
	s_add_i32 s68, 0, 0x1c000
	v_add_u32_e32 v142, s67, v205
	v_add_u32_e32 v162, s68, v205
	ds_read_b128 v[130:133], v142
	ds_read_b128 v[134:137], v142 offset:1024
	ds_read_b128 v[138:141], v142 offset:2048
	ds_read_b128 v[142:145], v142 offset:3072
	ds_read_b128 v[146:149], v162
	ds_read_b128 v[150:153], v162 offset:1024
	ds_read_b128 v[154:157], v162 offset:2048
	ds_read_b128 v[162:165], v162 offset:3072
	s_add_u32 s12, s22, 0x160000
	s_addc_u32 s13, s23, 0
	s_mov_b32 m0, s34
	ds_read_b128 v[166:169], v230 offset:32768
	ds_read_b128 v[170:173], v230 offset:33792
	ds_read_b128 v[184:187], v230 offset:34816
	ds_read_b128 v[188:191], v230 offset:35840
	ds_read_b128 v[192:195], v230 offset:36864
	ds_read_b128 v[196:199], v230 offset:37888
	ds_read_b128 v[200:203], v230 offset:38912
	ds_read_b128 v[232:235], v230 offset:39936
	global_load_lds_dwordx4 v174, s[12:13]
	s_mov_b32 m0, s35
	s_nop 0
	global_load_lds_dwordx4 v160, s[12:13]
	s_waitcnt vmcnt(8)
	s_waitcnt lgkmcnt(0)
	s_barrier
	s_setprio 1
	s_waitcnt lgkmcnt(0)
	v_mfma_f32_16x16x32_bf16 v[126:129], v[130:133], v[166:169], v[126:129]
	v_mfma_f32_16x16x32_bf16 v[126:129], v[134:137], v[170:173], v[126:129]
	v_mfma_f32_16x16x32_bf16 v[118:121], v[130:133], v[184:187], v[118:121]
	v_mfma_f32_16x16x32_bf16 v[118:121], v[134:137], v[188:191], v[118:121]
	v_mfma_f32_16x16x32_bf16 v[110:113], v[130:133], v[192:195], v[110:113]
	v_mfma_f32_16x16x32_bf16 v[110:113], v[134:137], v[196:199], v[110:113]
	v_mfma_f32_16x16x32_bf16 v[102:105], v[130:133], v[200:203], v[102:105]
	v_mfma_f32_16x16x32_bf16 v[102:105], v[134:137], v[232:235], v[102:105]
	v_mfma_f32_16x16x32_bf16 v[38:41], v[138:141], v[200:203], v[38:41]
	v_mfma_f32_16x16x32_bf16 v[38:41], v[142:145], v[232:235], v[38:41]
	v_mfma_f32_16x16x32_bf16 v[66:69], v[138:141], v[192:195], v[66:69]
	v_mfma_f32_16x16x32_bf16 v[66:69], v[142:145], v[196:199], v[66:69]
	v_mfma_f32_16x16x32_bf16 v[86:89], v[138:141], v[184:187], v[86:89]
	v_mfma_f32_16x16x32_bf16 v[86:89], v[142:145], v[188:191], v[86:89]
	v_mfma_f32_16x16x32_bf16 v[74:77], v[138:141], v[166:169], v[74:77]
	v_mfma_f32_16x16x32_bf16 v[74:77], v[142:145], v[170:173], v[74:77]
	v_mfma_f32_16x16x32_bf16 v[122:125], v[146:149], v[166:169], v[122:125]
	v_mfma_f32_16x16x32_bf16 v[122:125], v[150:153], v[170:173], v[122:125]
	v_mfma_f32_16x16x32_bf16 v[114:117], v[146:149], v[184:187], v[114:117]
	v_mfma_f32_16x16x32_bf16 v[114:117], v[150:153], v[188:191], v[114:117]
	v_mfma_f32_16x16x32_bf16 v[106:109], v[146:149], v[192:195], v[106:109]
	v_mfma_f32_16x16x32_bf16 v[106:109], v[150:153], v[196:199], v[106:109]
	v_mfma_f32_16x16x32_bf16 v[98:101], v[146:149], v[200:203], v[98:101]
	v_mfma_f32_16x16x32_bf16 v[98:101], v[150:153], v[232:235], v[98:101]
	v_mfma_f32_16x16x32_bf16 v[42:45], v[154:157], v[200:203], v[42:45]
	v_mfma_f32_16x16x32_bf16 v[42:45], v[162:165], v[232:235], v[42:45]
	v_mfma_f32_16x16x32_bf16 v[70:73], v[154:157], v[192:195], v[70:73]
	v_mfma_f32_16x16x32_bf16 v[70:73], v[162:165], v[196:199], v[70:73]
	v_mfma_f32_16x16x32_bf16 v[90:93], v[154:157], v[184:187], v[90:93]
	v_mfma_f32_16x16x32_bf16 v[90:93], v[162:165], v[188:191], v[90:93]
	v_mfma_f32_16x16x32_bf16 v[82:85], v[154:157], v[166:169], v[82:85]
	v_mfma_f32_16x16x32_bf16 v[82:85], v[162:165], v[170:173], v[82:85]
	s_setprio 0
	s_barrier
	s_add_i32 s12, s67, s33
	v_lshl_add_u64 v[212:213], v[212:213], 0, s[30:31]
	s_mov_b32 m0, s12
	ds_read_b128 v[166:169], v230 offset:49152
	ds_read_b128 v[170:173], v230 offset:50176
	ds_read_b128 v[184:187], v230 offset:51200
	ds_read_b128 v[188:191], v230 offset:52224
	ds_read_b128 v[192:195], v230 offset:53248
	ds_read_b128 v[196:199], v230 offset:54272
	ds_read_b128 v[200:203], v230 offset:55296
	ds_read_b128 v[232:235], v230 offset:56320
	global_load_lds_dwordx4 v[212:213], off
	s_add_i32 m0, s12, 0x2000
	s_add_u32 s12, s20, 0x160080
	v_lshl_add_u64 v[212:213], v[220:221], 0, s[30:31]
	s_addc_u32 s13, s21, 0
	s_add_i32 s20, s68, s33
	global_load_lds_dwordx4 v[212:213], off
	s_mov_b32 m0, s20
	s_nop 0
	global_load_lds_dwordx4 v0, s[12:13]
	s_add_i32 m0, s20, 0x2000
	s_nop 0
	global_load_lds_dwordx4 v158, s[12:13]
	v_lshl_add_u64 v[212:213], v[236:237], 0, s[30:31]
	s_mov_b32 m0, s55
	s_nop 0
	global_load_lds_dwordx4 v[212:213], off
	v_lshl_add_u64 v[212:213], v[238:239], 0, s[30:31]
	s_mov_b32 m0, s56
	s_nop 0
	global_load_lds_dwordx4 v[212:213], off
	s_waitcnt vmcnt(8)
	s_waitcnt lgkmcnt(0)
	s_barrier
	s_setprio 1
	s_waitcnt lgkmcnt(0)
	v_mfma_f32_16x16x32_bf16 v[58:61], v[154:157], v[166:169], v[58:61]
	v_mfma_f32_16x16x32_bf16 v[58:61], v[162:165], v[170:173], v[58:61]
	v_mfma_f32_16x16x32_bf16 v[34:37], v[154:157], v[184:187], v[34:37]
	v_mfma_f32_16x16x32_bf16 v[34:37], v[162:165], v[188:191], v[34:37]
	v_mfma_f32_16x16x32_bf16 v[14:17], v[154:157], v[192:195], v[14:17]
	v_mfma_f32_16x16x32_bf16 v[14:17], v[162:165], v[196:199], v[14:17]
	v_mfma_f32_16x16x32_bf16 v[6:9], v[154:157], v[200:203], v[6:9]
	v_mfma_f32_16x16x32_bf16 v[6:9], v[162:165], v[232:235], v[6:9]
	v_mfma_f32_16x16x32_bf16 v[18:21], v[146:149], v[200:203], v[18:21]
	v_mfma_f32_16x16x32_bf16 v[18:21], v[150:153], v[232:235], v[18:21]
	v_mfma_f32_16x16x32_bf16 v[26:29], v[146:149], v[192:195], v[26:29]
	v_mfma_f32_16x16x32_bf16 v[26:29], v[150:153], v[196:199], v[26:29]
	v_mfma_f32_16x16x32_bf16 v[54:57], v[146:149], v[184:187], v[54:57]
	v_mfma_f32_16x16x32_bf16 v[54:57], v[150:153], v[188:191], v[54:57]
	v_mfma_f32_16x16x32_bf16 v[78:81], v[146:149], v[166:169], v[78:81]
	v_mfma_f32_16x16x32_bf16 v[78:81], v[150:153], v[170:173], v[78:81]
	v_mfma_f32_16x16x32_bf16 v[50:53], v[138:141], v[166:169], v[50:53]
	v_mfma_f32_16x16x32_bf16 v[50:53], v[142:145], v[170:173], v[50:53]
	v_mfma_f32_16x16x32_bf16 v[30:33], v[138:141], v[184:187], v[30:33]
	v_mfma_f32_16x16x32_bf16 v[30:33], v[142:145], v[188:191], v[30:33]
	v_mfma_f32_16x16x32_bf16 v[10:13], v[138:141], v[192:195], v[10:13]
	v_mfma_f32_16x16x32_bf16 v[10:13], v[142:145], v[196:199], v[10:13]
	v_mfma_f32_16x16x32_bf16 v[2:5], v[138:141], v[200:203], v[2:5]
	v_mfma_f32_16x16x32_bf16 v[2:5], v[142:145], v[232:235], v[2:5]
	v_mfma_f32_16x16x32_bf16 v[22:25], v[130:133], v[200:203], v[22:25]
	v_mfma_f32_16x16x32_bf16 v[22:25], v[134:137], v[232:235], v[22:25]
	v_mfma_f32_16x16x32_bf16 v[46:49], v[130:133], v[192:195], v[46:49]
	v_mfma_f32_16x16x32_bf16 v[46:49], v[134:137], v[196:199], v[46:49]
	v_mfma_f32_16x16x32_bf16 v[62:65], v[130:133], v[184:187], v[62:65]
	v_mfma_f32_16x16x32_bf16 v[62:65], v[134:137], v[188:191], v[62:65]
	v_mfma_f32_16x16x32_bf16 v[94:97], v[130:133], v[166:169], v[94:97]
	v_mfma_f32_16x16x32_bf16 v[94:97], v[134:137], v[170:173], v[94:97]
	s_setprio 0
	s_barrier
	s_add_i32 s19, s19, 2
	s_add_u32 s15, s15, 0x100
	s_addc_u32 s18, s18, 0
	s_cmpk_gt_u32 s19, 0x55
	s_mov_b64 s[12:13], s[16:17]
	s_cbranch_scc0 .LBB0_2193
	v_readlane_b32 s12, v253, 2
	v_readlane_b32 s13, v253, 3
	s_and_b64 vcc, exec, s[12:13]
	s_cbranch_vccz .LBB0_2196
	s_barrier
